# C1 recipe + MFMA order changed so each accumulator's k=0 and k=1 MFMAs are back-to-back (SrcC forwarding, same per-accumulator order, bit-identical)
# speedup vs baseline: 1.0123x; 1.0107x over previous
; #define PG8_STAGE(bufoff, gbase, voff) do { _Pragma("unroll") for (int _i = 0; _i < 2; ++_i) \
;         __builtin_amdgcn_global_load_lds((const unsigned*)((const char*)(gbase) + (voff)[_i]), (PG8_LAS unsigned*)(lds + (bufoff) + ldsw + _i * 8192), 16, 0, 0); } while (0)
; #define PG8_LDA(dst, b, h) do { _Pragma("unroll") for (int m = 0; m < 4; ++m) _Pragma("unroll") for (int k = 0; k < 2; ++k) dst[m][k] = *(const PG8_LAS bf16x8*)(lds + PG8_SA(b, h) + aoff + m * 2048 + k * 1024); } while (0)
; #define PG8_LDB(dst, b, h) do { _Pragma("unroll") for (int n = 0; n < 2; ++n) _Pragma("unroll") for (int k = 0; k < 2; ++k) dst[n][k] = *(const PG8_LAS bf16x8*)(lds + PG8_SB(b, h) + boff + n * 2048 + k * 1024); } while (0)
; #define PG8_MMA(ai, bj, At, Bt) do { __builtin_amdgcn_s_setprio(1); _Pragma("unroll") for (int m = 0; m < 4; ++m) _Pragma("unroll") for (int n = 0; n < 2; ++n) _Pragma("unroll") for (int k = 0; k < 2; ++k) \
;         acc[ai][bj][m][n] = __builtin_amdgcn_mfma_f32_16x16x32_bf16(Bt[n][k], At[m][k], acc[ai][bj][m][n], 0, 0, 0); __builtin_amdgcn_s_setprio(0); } while (0)
; #define PG8_WAIT_V(n) asm volatile("s_waitcnt vmcnt(" #n ")" ::: "memory")
; #define PG8_WAIT_L(n) asm volatile("s_waitcnt lgkmcnt(" #n ")" ::: "memory")
; #define PG8_BAR __builtin_amdgcn_s_barrier()
; #define PG8_SCHED __builtin_amdgcn_sched_barrier(0)
; template <class Epi, class Sched, bool ALIGN_EPI = false, bool SP2 = false, bool ABLK = false, bool BBLK = false>
; __device__ __forceinline__ void gemm_phase(PG8_LAS unsigned char* lds, const Gemm g, const Sched& S, const Epi& E) {
;     ...
;             PG8_LDB(B0, 0, 0); PG8_LDB(B1, 0, 1); PG8_SCHED; PG8_LDA(At, 0, 0); PG8_STAGE(PG8_SA(1, 1), a1 + hstepA, voffA);
;             PG8_WAIT_V(8); PG8_WAIT_L(0); PG8_BAR; PG8_MMA(0, 0, At, B0); PG8_MMA(0, 1, At, B1); PG8_BAR; PG8_SCHED;
;             PG8_LDA(At, 0, 1); PG8_STAGE(PG8_SB(0, 0), b2, voffB); PG8_STAGE(PG8_SB(0, 1), b2 + hstepB, voffB); PG8_STAGE(PG8_SA(0, 0), a2, voffA);
;             PG8_WAIT_V(8); PG8_WAIT_L(0); PG8_BAR; PG8_MMA(1, 0, At, B0); PG8_MMA(1, 1, At, B1); PG8_BAR; PG8_SCHED;
.LBB0_185:
	s_add_u32 s13, s20, 0x4000
	s_addc_u32 s22, s21, 0
	s_cmp_eq_u32 vcc_hi, 28
	s_cselect_b32 s26, s70, s13
	s_cselect_b32 s27, s9, s22
	s_cselect_b32 s24, s71, s77
	s_cselect_b32 s25, s7, vcc_lo
	s_add_u32 s22, s26, 0x8000
	s_addc_u32 s23, s27, 0
	s_add_i32 s13, 0, 0x10000
	v_add_u32_e32 v36, s13, v160
	s_add_i32 s88, 0, 0x14000
	ds_read_b128 v[152:155], v36
	ds_read_b128 v[156:159], v36 offset:1024
	ds_read_b128 v[162:165], v36 offset:2048
	ds_read_b128 v[166:169], v36 offset:3072
	v_add_u32_e32 v36, s88, v160
	ds_read_b128 v[170:173], v36
	ds_read_b128 v[174:177], v36 offset:1024
	ds_read_b128 v[178:181], v36 offset:2048
	ds_read_b128 v[182:185], v36 offset:3072
	s_add_i32 m0, s19, 0xc000
	ds_read_b128 v[186:189], v161
	ds_read_b128 v[190:193], v161 offset:1024
	ds_read_b128 v[194:197], v161 offset:2048
	ds_read_b128 v[198:201], v161 offset:3072
	ds_read_b128 v[202:205], v161 offset:4096
	ds_read_b128 v[206:209], v161 offset:5120
	ds_read_b128 v[210:213], v161 offset:6144
	ds_read_b128 v[214:217], v161 offset:7168
	global_load_lds_dwordx4 v148, s[20:21]
	s_add_i32 m0, s19, 0xe000
	s_nop 0
	global_load_lds_dwordx4 v150, s[20:21]
	s_waitcnt vmcnt(8)
	s_waitcnt lgkmcnt(0)
	v_mfma_f32_16x16x32_bf16 v[132:135], v[152:155], v[186:189], v[132:135]
	v_mfma_f32_16x16x32_bf16 v[132:135], v[156:159], v[190:193], v[132:135]
	v_mfma_f32_16x16x32_bf16 v[128:131], v[162:165], v[186:189], v[128:131]
	v_mfma_f32_16x16x32_bf16 v[128:131], v[166:169], v[190:193], v[128:131]
	s_barrier
	s_setprio 1
	v_mfma_f32_16x16x32_bf16 v[116:119], v[152:155], v[194:197], v[116:119]
	v_mfma_f32_16x16x32_bf16 v[116:119], v[156:159], v[198:201], v[116:119]
	v_mfma_f32_16x16x32_bf16 v[112:115], v[162:165], v[194:197], v[112:115]
	v_mfma_f32_16x16x32_bf16 v[112:115], v[166:169], v[198:201], v[112:115]
	v_mfma_f32_16x16x32_bf16 v[100:103], v[152:155], v[202:205], v[100:103]
	v_mfma_f32_16x16x32_bf16 v[100:103], v[156:159], v[206:209], v[100:103]
	v_mfma_f32_16x16x32_bf16 v[96:99], v[162:165], v[202:205], v[96:99]
	v_mfma_f32_16x16x32_bf16 v[96:99], v[166:169], v[206:209], v[96:99]
	v_mfma_f32_16x16x32_bf16 v[84:87], v[152:155], v[210:213], v[84:87]
	v_mfma_f32_16x16x32_bf16 v[84:87], v[156:159], v[214:217], v[84:87]
	v_mfma_f32_16x16x32_bf16 v[80:83], v[162:165], v[210:213], v[80:83]
	v_mfma_f32_16x16x32_bf16 v[80:83], v[166:169], v[214:217], v[80:83]
	s_setprio 0
	s_setprio 1
	v_mfma_f32_16x16x32_bf16 v[124:127], v[170:173], v[186:189], v[124:127]
	v_mfma_f32_16x16x32_bf16 v[124:127], v[174:177], v[190:193], v[124:127]
	v_mfma_f32_16x16x32_bf16 v[120:123], v[178:181], v[186:189], v[120:123]
	v_mfma_f32_16x16x32_bf16 v[120:123], v[182:185], v[190:193], v[120:123]
	v_mfma_f32_16x16x32_bf16 v[108:111], v[170:173], v[194:197], v[108:111]
	v_mfma_f32_16x16x32_bf16 v[108:111], v[174:177], v[198:201], v[108:111]
	v_mfma_f32_16x16x32_bf16 v[104:107], v[178:181], v[194:197], v[104:107]
	v_mfma_f32_16x16x32_bf16 v[104:107], v[182:185], v[198:201], v[104:107]
	v_mfma_f32_16x16x32_bf16 v[92:95], v[170:173], v[202:205], v[92:95]
	v_mfma_f32_16x16x32_bf16 v[92:95], v[174:177], v[206:209], v[92:95]
	v_mfma_f32_16x16x32_bf16 v[88:91], v[178:181], v[202:205], v[88:91]
	v_mfma_f32_16x16x32_bf16 v[88:91], v[182:185], v[206:209], v[88:91]
	v_mfma_f32_16x16x32_bf16 v[76:79], v[170:173], v[210:213], v[76:79]
	v_mfma_f32_16x16x32_bf16 v[76:79], v[174:177], v[214:217], v[76:79]
	v_mfma_f32_16x16x32_bf16 v[72:75], v[178:181], v[210:213], v[72:75]
	v_mfma_f32_16x16x32_bf16 v[72:75], v[182:185], v[214:217], v[72:75]
	s_setprio 0
	s_barrier
	s_add_i32 s13, s13, s31
	s_mov_b32 m0, s13
	ds_read_b128 v[186:189], v161 offset:16384
	ds_read_b128 v[190:193], v161 offset:17408
	ds_read_b128 v[194:197], v161 offset:18432
	ds_read_b128 v[198:201], v161 offset:19456
	ds_read_b128 v[202:205], v161 offset:20480
	ds_read_b128 v[206:209], v161 offset:21504
	ds_read_b128 v[210:213], v161 offset:22528
	ds_read_b128 v[214:217], v161 offset:23552
	global_load_lds_dwordx4 v140, s[24:25]
	s_add_i32 m0, s13, 0x2000
	s_add_u32 s68, s24, 0x4000
	s_addc_u32 s69, s25, 0
	s_add_i32 s13, s88, s31
	global_load_lds_dwordx4 v136, s[24:25]
	s_mov_b32 m0, s13
	s_nop 0
	global_load_lds_dwordx4 v140, s[68:69]
	s_add_i32 m0, s13, 0x2000
	s_nop 0
	global_load_lds_dwordx4 v136, s[68:69]
	s_mov_b32 m0, s19
	s_nop 0
	global_load_lds_dwordx4 v142, s[26:27]
	s_mov_b32 m0, s35
	s_nop 0
	global_load_lds_dwordx4 v138, s[26:27]
	s_waitcnt vmcnt(8)
	s_waitcnt lgkmcnt(0)
	v_mfma_f32_16x16x32_bf16 v[68:71], v[152:155], v[186:189], v[68:71]
	v_mfma_f32_16x16x32_bf16 v[68:71], v[156:159], v[190:193], v[68:71]
	v_mfma_f32_16x16x32_bf16 v[64:67], v[162:165], v[186:189], v[64:67]
	v_mfma_f32_16x16x32_bf16 v[64:67], v[166:169], v[190:193], v[64:67]
	s_barrier
; #define PG8_STAGE(bufoff, gbase, voff) do { _Pragma("unroll") for (int _i = 0; _i < 2; ++_i) \
;         __builtin_amdgcn_global_load_lds((const unsigned*)((const char*)(gbase) + (voff)[_i]), (PG8_LAS unsigned*)(lds + (bufoff) + ldsw + _i * 8192), 16, 0, 0); } while (0)
; #define PG8_LDA(dst, b, h) do { _Pragma("unroll") for (int m = 0; m < 4; ++m) _Pragma("unroll") for (int k = 0; k < 2; ++k) dst[m][k] = *(const PG8_LAS bf16x8*)(lds + PG8_SA(b, h) + aoff + m * 2048 + k * 1024); } while (0)
; #define PG8_LDB(dst, b, h) do { _Pragma("unroll") for (int n = 0; n < 2; ++n) _Pragma("unroll") for (int k = 0; k < 2; ++k) dst[n][k] = *(const PG8_LAS bf16x8*)(lds + PG8_SB(b, h) + boff + n * 2048 + k * 1024); } while (0)
; #define PG8_MMA(ai, bj, At, Bt) do { __builtin_amdgcn_s_setprio(1); _Pragma("unroll") for (int m = 0; m < 4; ++m) _Pragma("unroll") for (int n = 0; n < 2; ++n) _Pragma("unroll") for (int k = 0; k < 2; ++k) \
;         acc[ai][bj][m][n] = __builtin_amdgcn_mfma_f32_16x16x32_bf16(Bt[n][k], At[m][k], acc[ai][bj][m][n], 0, 0, 0); __builtin_amdgcn_s_setprio(0); } while (0)
; #define PG8_WAIT_V(n) asm volatile("s_waitcnt vmcnt(" #n ")" ::: "memory")
; #define PG8_WAIT_L(n) asm volatile("s_waitcnt lgkmcnt(" #n ")" ::: "memory")
; #define PG8_BAR __builtin_amdgcn_s_barrier()
; #define PG8_SCHED __builtin_amdgcn_sched_barrier(0)
; template <class Epi, class Sched, bool ALIGN_EPI = false, bool SP2 = false, bool ABLK = false, bool BBLK = false>
; __device__ __forceinline__ void gemm_phase(PG8_LAS unsigned char* lds, const Gemm g, const Sched& S, const Epi& E) {
;     ...
;             PG8_WAIT_V(8); PG8_WAIT_L(0); PG8_BAR; PG8_MMA(1, 0, At, B0); PG8_MMA(1, 1, At, B1); PG8_BAR; PG8_SCHED;
;             PG8_LDB(B0, 1, 0); PG8_LDB(B1, 1, 1); PG8_SCHED; PG8_LDA(At, 1, 0); PG8_STAGE(PG8_SA(0, 1), a2 + hstepA, voffA);
;             PG8_WAIT_V(8); PG8_WAIT_L(0); PG8_BAR; PG8_MMA(0, 0, At, B0); PG8_MMA(0, 1, At, B1); PG8_BAR; PG8_SCHED;
;             PG8_LDA(At, 1, 1); PG8_STAGE(PG8_SB(1, 0), b3, voffB); PG8_STAGE(PG8_SB(1, 1), b3 + hstepB, voffB); PG8_STAGE(PG8_SA(1, 0), a3, voffA);
;             PG8_WAIT_V(8); PG8_WAIT_L(0); PG8_BAR; PG8_MMA(1, 0, At, B0); PG8_MMA(1, 1, At, B1); PG8_BAR; PG8_SCHED;
	s_setprio 1
	v_mfma_f32_16x16x32_bf16 v[52:55], v[152:155], v[194:197], v[52:55]
	v_mfma_f32_16x16x32_bf16 v[52:55], v[156:159], v[198:201], v[52:55]
	v_mfma_f32_16x16x32_bf16 v[48:51], v[162:165], v[194:197], v[48:51]
	v_mfma_f32_16x16x32_bf16 v[48:51], v[166:169], v[198:201], v[48:51]
	v_mfma_f32_16x16x32_bf16 v[32:35], v[152:155], v[202:205], v[32:35]
	v_mfma_f32_16x16x32_bf16 v[32:35], v[156:159], v[206:209], v[32:35]
	v_mfma_f32_16x16x32_bf16 v[28:31], v[162:165], v[202:205], v[28:31]
	v_mfma_f32_16x16x32_bf16 v[28:31], v[166:169], v[206:209], v[28:31]
	v_mfma_f32_16x16x32_bf16 v[16:19], v[152:155], v[210:213], v[16:19]
	v_mfma_f32_16x16x32_bf16 v[16:19], v[156:159], v[214:217], v[16:19]
	v_mfma_f32_16x16x32_bf16 v[12:15], v[162:165], v[210:213], v[12:15]
	v_mfma_f32_16x16x32_bf16 v[12:15], v[166:169], v[214:217], v[12:15]
	s_setprio 0
	s_setprio 1
	v_mfma_f32_16x16x32_bf16 v[60:63], v[170:173], v[186:189], v[60:63]
	v_mfma_f32_16x16x32_bf16 v[60:63], v[174:177], v[190:193], v[60:63]
	v_mfma_f32_16x16x32_bf16 v[56:59], v[178:181], v[186:189], v[56:59]
	v_mfma_f32_16x16x32_bf16 v[56:59], v[182:185], v[190:193], v[56:59]
	v_mfma_f32_16x16x32_bf16 v[44:47], v[170:173], v[194:197], v[44:47]
	v_mfma_f32_16x16x32_bf16 v[44:47], v[174:177], v[198:201], v[44:47]
	v_mfma_f32_16x16x32_bf16 v[40:43], v[178:181], v[194:197], v[40:43]
	v_mfma_f32_16x16x32_bf16 v[40:43], v[182:185], v[198:201], v[40:43]
	v_mfma_f32_16x16x32_bf16 v[24:27], v[170:173], v[202:205], v[24:27]
	v_mfma_f32_16x16x32_bf16 v[24:27], v[174:177], v[206:209], v[24:27]
	v_mfma_f32_16x16x32_bf16 v[20:23], v[178:181], v[202:205], v[20:23]
	v_mfma_f32_16x16x32_bf16 v[20:23], v[182:185], v[206:209], v[20:23]
	v_mfma_f32_16x16x32_bf16 v[8:11], v[170:173], v[210:213], v[8:11]
	v_mfma_f32_16x16x32_bf16 v[8:11], v[174:177], v[214:217], v[8:11]
	v_mfma_f32_16x16x32_bf16 v[4:7], v[178:181], v[210:213], v[4:7]
	v_mfma_f32_16x16x32_bf16 v[4:7], v[182:185], v[214:217], v[4:7]
	s_setprio 0
	s_barrier
	s_add_i32 s13, 0, 0x18000
	v_add_u32_e32 v36, s13, v160
	s_add_i32 s68, 0, 0x1c000
	ds_read_b128 v[152:155], v36
	ds_read_b128 v[156:159], v36 offset:1024
	ds_read_b128 v[162:165], v36 offset:2048
	ds_read_b128 v[166:169], v36 offset:3072
	v_add_u32_e32 v36, s68, v160
	ds_read_b128 v[170:173], v36
	ds_read_b128 v[174:177], v36 offset:1024
	ds_read_b128 v[178:181], v36 offset:2048
	ds_read_b128 v[182:185], v36 offset:3072
	s_add_u32 s26, s26, 0x4000
	s_addc_u32 s27, s27, 0
	s_mov_b32 m0, s36
	ds_read_b128 v[186:189], v161 offset:32768
	ds_read_b128 v[190:193], v161 offset:33792
	ds_read_b128 v[194:197], v161 offset:34816
	ds_read_b128 v[198:201], v161 offset:35840
	ds_read_b128 v[202:205], v161 offset:36864
	ds_read_b128 v[206:209], v161 offset:37888
	ds_read_b128 v[210:213], v161 offset:38912
	ds_read_b128 v[214:217], v161 offset:39936
	global_load_lds_dwordx4 v142, s[26:27]
	s_mov_b32 m0, s37
	s_nop 0
	global_load_lds_dwordx4 v138, s[26:27]
	s_waitcnt vmcnt(8)
	s_waitcnt lgkmcnt(0)
	v_mfma_f32_16x16x32_bf16 v[132:135], v[152:155], v[186:189], v[132:135]
	v_mfma_f32_16x16x32_bf16 v[132:135], v[156:159], v[190:193], v[132:135]
	v_mfma_f32_16x16x32_bf16 v[128:131], v[162:165], v[186:189], v[128:131]
	v_mfma_f32_16x16x32_bf16 v[128:131], v[166:169], v[190:193], v[128:131]
	s_barrier
	s_setprio 1
	v_mfma_f32_16x16x32_bf16 v[116:119], v[152:155], v[194:197], v[116:119]
	v_mfma_f32_16x16x32_bf16 v[116:119], v[156:159], v[198:201], v[116:119]
	v_mfma_f32_16x16x32_bf16 v[112:115], v[162:165], v[194:197], v[112:115]
	v_mfma_f32_16x16x32_bf16 v[112:115], v[166:169], v[198:201], v[112:115]
	v_mfma_f32_16x16x32_bf16 v[100:103], v[152:155], v[202:205], v[100:103]
	v_mfma_f32_16x16x32_bf16 v[100:103], v[156:159], v[206:209], v[100:103]
	v_mfma_f32_16x16x32_bf16 v[96:99], v[162:165], v[202:205], v[96:99]
	v_mfma_f32_16x16x32_bf16 v[96:99], v[166:169], v[206:209], v[96:99]
	v_mfma_f32_16x16x32_bf16 v[84:87], v[152:155], v[210:213], v[84:87]
	v_mfma_f32_16x16x32_bf16 v[84:87], v[156:159], v[214:217], v[84:87]
	v_mfma_f32_16x16x32_bf16 v[80:83], v[162:165], v[210:213], v[80:83]
	v_mfma_f32_16x16x32_bf16 v[80:83], v[166:169], v[214:217], v[80:83]
	s_setprio 0
	s_setprio 1
	v_mfma_f32_16x16x32_bf16 v[124:127], v[170:173], v[186:189], v[124:127]
	v_mfma_f32_16x16x32_bf16 v[124:127], v[174:177], v[190:193], v[124:127]
	v_mfma_f32_16x16x32_bf16 v[120:123], v[178:181], v[186:189], v[120:123]
	v_mfma_f32_16x16x32_bf16 v[120:123], v[182:185], v[190:193], v[120:123]
	v_mfma_f32_16x16x32_bf16 v[108:111], v[170:173], v[194:197], v[108:111]
	v_mfma_f32_16x16x32_bf16 v[108:111], v[174:177], v[198:201], v[108:111]
	v_mfma_f32_16x16x32_bf16 v[104:107], v[178:181], v[194:197], v[104:107]
	v_mfma_f32_16x16x32_bf16 v[104:107], v[182:185], v[198:201], v[104:107]
	v_mfma_f32_16x16x32_bf16 v[92:95], v[170:173], v[202:205], v[92:95]
	v_mfma_f32_16x16x32_bf16 v[92:95], v[174:177], v[206:209], v[92:95]
	v_mfma_f32_16x16x32_bf16 v[88:91], v[178:181], v[202:205], v[88:91]
	v_mfma_f32_16x16x32_bf16 v[88:91], v[182:185], v[206:209], v[88:91]
	v_mfma_f32_16x16x32_bf16 v[76:79], v[170:173], v[210:213], v[76:79]
	v_mfma_f32_16x16x32_bf16 v[76:79], v[174:177], v[214:217], v[76:79]
	v_mfma_f32_16x16x32_bf16 v[72:75], v[178:181], v[210:213], v[72:75]
	v_mfma_f32_16x16x32_bf16 v[72:75], v[182:185], v[214:217], v[72:75]
	s_setprio 0
	s_barrier
; #define PG8_STAGE(bufoff, gbase, voff) do { _Pragma("unroll") for (int _i = 0; _i < 2; ++_i) \
;         __builtin_amdgcn_global_load_lds((const unsigned*)((const char*)(gbase) + (voff)[_i]), (PG8_LAS unsigned*)(lds + (bufoff) + ldsw + _i * 8192), 16, 0, 0); } while (0)
; #define PG8_LDA(dst, b, h) do { _Pragma("unroll") for (int m = 0; m < 4; ++m) _Pragma("unroll") for (int k = 0; k < 2; ++k) dst[m][k] = *(const PG8_LAS bf16x8*)(lds + PG8_SA(b, h) + aoff + m * 2048 + k * 1024); } while (0)
; #define PG8_MMA(ai, bj, At, Bt) do { __builtin_amdgcn_s_setprio(1); _Pragma("unroll") for (int m = 0; m < 4; ++m) _Pragma("unroll") for (int n = 0; n < 2; ++n) _Pragma("unroll") for (int k = 0; k < 2; ++k) \
;         acc[ai][bj][m][n] = __builtin_amdgcn_mfma_f32_16x16x32_bf16(Bt[n][k], At[m][k], acc[ai][bj][m][n], 0, 0, 0); __builtin_amdgcn_s_setprio(0); } while (0)
; #define PG8_WAIT_V(n) asm volatile("s_waitcnt vmcnt(" #n ")" ::: "memory")
; #define PG8_WAIT_L(n) asm volatile("s_waitcnt lgkmcnt(" #n ")" ::: "memory")
; #define PG8_BAR __builtin_amdgcn_s_barrier()
; #define PG8_SCHED __builtin_amdgcn_sched_barrier(0)
; template <class Epi, class Sched, bool ALIGN_EPI = false, bool SP2 = false, bool ABLK = false, bool BBLK = false>
; __device__ __forceinline__ void gemm_phase(PG8_LAS unsigned char* lds, const Gemm g, const Sched& S, const Epi& E) {
;     ...
;         for (int t = 0; t < nt; t += 2) {
;             const bool last = (t == nt - 2);
;             const char* a1 = cA + (size_t)(t + 1) * kstepA;
;             const char* a2 = last ? nA : cA + (size_t)(t + 2) * kstepA; const char* b2 = last ? nB : cB + (size_t)(t + 2) * kstepB;
;             const char* a3 = a2 + kstepA; const char* b3 = b2 + kstepB;
;     ...
;             PG8_LDA(At, 1, 1); PG8_STAGE(PG8_SB(1, 0), b3, voffB); PG8_STAGE(PG8_SB(1, 1), b3 + hstepB, voffB); PG8_STAGE(PG8_SA(1, 0), a3, voffA);
;             PG8_WAIT_V(8); PG8_WAIT_L(0); PG8_BAR; PG8_MMA(1, 0, At, B0); PG8_MMA(1, 1, At, B1); PG8_BAR; PG8_SCHED;
	s_add_u32 s26, s24, 0x8000
	s_addc_u32 s27, s25, 0
	s_add_i32 s13, s13, s31
	s_mov_b32 m0, s13
	ds_read_b128 v[186:189], v161 offset:49152
	ds_read_b128 v[190:193], v161 offset:50176
	ds_read_b128 v[194:197], v161 offset:51200
	ds_read_b128 v[198:201], v161 offset:52224
	ds_read_b128 v[202:205], v161 offset:53248
	ds_read_b128 v[206:209], v161 offset:54272
	ds_read_b128 v[210:213], v161 offset:55296
	ds_read_b128 v[214:217], v161 offset:56320
	global_load_lds_dwordx4 v140, s[26:27]
	s_add_i32 m0, s13, 0x2000
	s_add_u32 s24, s24, 0xc000
	s_addc_u32 s25, s25, 0
	s_add_i32 s13, s68, s31
	global_load_lds_dwordx4 v136, s[26:27]
	s_mov_b32 m0, s13
	s_nop 0
	global_load_lds_dwordx4 v140, s[24:25]
	s_add_i32 m0, s13, 0x2000
	s_nop 0
	global_load_lds_dwordx4 v136, s[24:25]
	s_mov_b32 m0, s62
	s_nop 0
	global_load_lds_dwordx4 v142, s[22:23]
	s_mov_b32 m0, s63
	s_nop 0
	global_load_lds_dwordx4 v138, s[22:23]
	s_waitcnt vmcnt(8)
	s_waitcnt lgkmcnt(0)
	v_mfma_f32_16x16x32_bf16 v[68:71], v[152:155], v[186:189], v[68:71]
	v_mfma_f32_16x16x32_bf16 v[68:71], v[156:159], v[190:193], v[68:71]
	v_mfma_f32_16x16x32_bf16 v[64:67], v[162:165], v[186:189], v[64:67]
	v_mfma_f32_16x16x32_bf16 v[64:67], v[166:169], v[190:193], v[64:67]
	s_barrier
	s_setprio 1
	v_mfma_f32_16x16x32_bf16 v[52:55], v[152:155], v[194:197], v[52:55]
	v_mfma_f32_16x16x32_bf16 v[52:55], v[156:159], v[198:201], v[52:55]
	v_mfma_f32_16x16x32_bf16 v[48:51], v[162:165], v[194:197], v[48:51]
	v_mfma_f32_16x16x32_bf16 v[48:51], v[166:169], v[198:201], v[48:51]
	v_mfma_f32_16x16x32_bf16 v[32:35], v[152:155], v[202:205], v[32:35]
	v_mfma_f32_16x16x32_bf16 v[32:35], v[156:159], v[206:209], v[32:35]
	v_mfma_f32_16x16x32_bf16 v[28:31], v[162:165], v[202:205], v[28:31]
	v_mfma_f32_16x16x32_bf16 v[28:31], v[166:169], v[206:209], v[28:31]
	v_mfma_f32_16x16x32_bf16 v[16:19], v[152:155], v[210:213], v[16:19]
	v_mfma_f32_16x16x32_bf16 v[16:19], v[156:159], v[214:217], v[16:19]
	v_mfma_f32_16x16x32_bf16 v[12:15], v[162:165], v[210:213], v[12:15]
	v_mfma_f32_16x16x32_bf16 v[12:15], v[166:169], v[214:217], v[12:15]
	s_setprio 0
	s_setprio 1
	v_mfma_f32_16x16x32_bf16 v[60:63], v[170:173], v[186:189], v[60:63]
	v_mfma_f32_16x16x32_bf16 v[60:63], v[174:177], v[190:193], v[60:63]
	v_mfma_f32_16x16x32_bf16 v[56:59], v[178:181], v[186:189], v[56:59]
	v_mfma_f32_16x16x32_bf16 v[56:59], v[182:185], v[190:193], v[56:59]
	v_mfma_f32_16x16x32_bf16 v[44:47], v[170:173], v[194:197], v[44:47]
	v_mfma_f32_16x16x32_bf16 v[44:47], v[174:177], v[198:201], v[44:47]
	v_mfma_f32_16x16x32_bf16 v[40:43], v[178:181], v[194:197], v[40:43]
	v_mfma_f32_16x16x32_bf16 v[40:43], v[182:185], v[198:201], v[40:43]
	v_mfma_f32_16x16x32_bf16 v[24:27], v[170:173], v[202:205], v[24:27]
	v_mfma_f32_16x16x32_bf16 v[24:27], v[174:177], v[206:209], v[24:27]
	v_mfma_f32_16x16x32_bf16 v[20:23], v[178:181], v[202:205], v[20:23]
	v_mfma_f32_16x16x32_bf16 v[20:23], v[182:185], v[206:209], v[20:23]
	v_mfma_f32_16x16x32_bf16 v[8:11], v[170:173], v[210:213], v[8:11]
	v_mfma_f32_16x16x32_bf16 v[8:11], v[174:177], v[214:217], v[8:11]
	v_mfma_f32_16x16x32_bf16 v[4:7], v[178:181], v[210:213], v[4:7]
	v_mfma_f32_16x16x32_bf16 v[4:7], v[182:185], v[214:217], v[4:7]
	s_setprio 0
	s_barrier
	s_add_i32 vcc_hi, vcc_hi, 2
	s_add_u32 s20, s20, 0x10000
	s_addc_u32 s21, s21, 0
	s_add_u32 s77, s77, 0x10000
	s_addc_u32 vcc_lo, vcc_lo, 0
	s_cmp_gt_u32 vcc_hi, 29
	s_cbranch_scc0 .LBB0_185
	s_and_b64 vcc, exec, s[4:5]
	s_cbranch_vccz .LBB0_188
	s_barrier

; #define PG8_STAGE(bufoff, gbase, voff) do { _Pragma("unroll") for (int _i = 0; _i < 2; ++_i) \
;         __builtin_amdgcn_global_load_lds((const unsigned*)((const char*)(gbase) + (voff)[_i]), (PG8_LAS unsigned*)(lds + (bufoff) + ldsw + _i * 8192), 16, 0, 0); } while (0)
; #define PG8_LDA(dst, b, h) do { _Pragma("unroll") for (int m = 0; m < 4; ++m) _Pragma("unroll") for (int k = 0; k < 2; ++k) dst[m][k] = *(const PG8_LAS bf16x8*)(lds + PG8_SA(b, h) + aoff + m * 2048 + k * 1024); } while (0)
; #define PG8_LDB(dst, b, h) do { _Pragma("unroll") for (int n = 0; n < 2; ++n) _Pragma("unroll") for (int k = 0; k < 2; ++k) dst[n][k] = *(const PG8_LAS bf16x8*)(lds + PG8_SB(b, h) + boff + n * 2048 + k * 1024); } while (0)
; #define PG8_MMA(ai, bj, At, Bt) do { __builtin_amdgcn_s_setprio(1); _Pragma("unroll") for (int m = 0; m < 4; ++m) _Pragma("unroll") for (int n = 0; n < 2; ++n) _Pragma("unroll") for (int k = 0; k < 2; ++k) \
;         acc[ai][bj][m][n] = __builtin_amdgcn_mfma_f32_16x16x32_bf16(Bt[n][k], At[m][k], acc[ai][bj][m][n], 0, 0, 0); __builtin_amdgcn_s_setprio(0); } while (0)
; #define PG8_WAIT_V(n) asm volatile("s_waitcnt vmcnt(" #n ")" ::: "memory")
; template <class Epi, class Sched, bool ALIGN_EPI = false, bool SP2 = false, bool ABLK = false, bool BBLK = false>
; __device__ __forceinline__ void gemm_phase(PG8_LAS unsigned char* lds, const Gemm g, const Sched& S, const Epi& E) {
;     ...
;         for (int t = 0; t < nt; t += 2) {
;             const bool last = (t == nt - 2);
;             const char* a1 = cA + (size_t)(t + 1) * kstepA;
;             const char* a2 = last ? nA : cA + (size_t)(t + 2) * kstepA; const char* b2 = last ? nB : cB + (size_t)(t + 2) * kstepB;
;             const char* a3 = a2 + kstepA; const char* b3 = b2 + kstepB;
;             if (last && has_next) S.a_ready(nxt);
;             if constexpr (SP2) {
;             PG8_LDB(B0, 0, 0); PG8_LDB(B1, 0, 1); PG8_SCHED; PG8_LDA(At, 0, 0); PG8_STAGE(PG8_SA(1, 1), a1 + hstepA, voffA);
;             PG8_WAIT_V(8); PG8_WAIT_L(0); PG8_BAR; PG8_MMA(0, 0, At, B0); PG8_MMA(0, 1, At, B1); PG8_BAR; PG8_SCHED;
;             PG8_LDA(At, 0, 1); PG8_STAGE(PG8_SB(0, 0), b2, voffB); PG8_STAGE(PG8_SB(0, 1), b2 + hstepB, voffB); PG8_STAGE(PG8_SA(0, 0), a2, voffA);
;             PG8_WAIT_V(8); PG8_WAIT_L(0); PG8_BAR; PG8_MMA(1, 0, At, B0); PG8_MMA(1, 1, At, B1); PG8_BAR; PG8_SCHED;
.LBB0_439:
	s_add_u32 s16, s10, 0x4000
	s_addc_u32 s17, s11, 0
	s_cmpk_eq_i32 s13, 0x54
	s_cselect_b32 s20, s0, s16
	s_cselect_b32 s21, s1, s17
	s_cselect_b32 s18, s8, vcc_lo
	s_cselect_b32 s19, s9, vcc_hi
	s_add_u32 s16, s20, 0x8000
	s_addc_u32 s17, s21, 0
	s_add_i32 s68, 0, 0x10000
	v_add_u32_e32 v36, s68, v148
	s_add_i32 s88, 0, 0x14000
	ds_read_b128 v[152:155], v36
	ds_read_b128 v[156:159], v36 offset:1024
	ds_read_b128 v[160:163], v36 offset:2048
	ds_read_b128 v[164:167], v36 offset:3072
	v_add_u32_e32 v36, s88, v148
	ds_read_b128 v[168:171], v36
	ds_read_b128 v[172:175], v36 offset:1024
	ds_read_b128 v[176:179], v36 offset:2048
	ds_read_b128 v[180:183], v36 offset:3072
	s_add_i32 m0, s27, 0xc000
	ds_read_b128 v[184:187], v150
	ds_read_b128 v[188:191], v150 offset:1024
	ds_read_b128 v[192:195], v150 offset:2048
	ds_read_b128 v[196:199], v150 offset:3072
	ds_read_b128 v[200:203], v150 offset:4096
	ds_read_b128 v[204:207], v150 offset:5120
	ds_read_b128 v[208:211], v150 offset:6144
	ds_read_b128 v[212:215], v150 offset:7168
	global_load_lds_dwordx4 v144, s[10:11]
	s_add_i32 m0, s27, 0xe000
	s_nop 0
	global_load_lds_dwordx4 v146, s[10:11]
	s_waitcnt vmcnt(8)
	s_waitcnt lgkmcnt(0)
	v_mfma_f32_16x16x32_bf16 v[132:135], v[152:155], v[184:187], v[132:135]
	v_mfma_f32_16x16x32_bf16 v[132:135], v[156:159], v[188:191], v[132:135]
	v_mfma_f32_16x16x32_bf16 v[128:131], v[160:163], v[184:187], v[128:131]
	v_mfma_f32_16x16x32_bf16 v[128:131], v[164:167], v[188:191], v[128:131]
	s_barrier
	s_setprio 1
	v_mfma_f32_16x16x32_bf16 v[124:127], v[152:155], v[192:195], v[124:127]
	v_mfma_f32_16x16x32_bf16 v[124:127], v[156:159], v[196:199], v[124:127]
	v_mfma_f32_16x16x32_bf16 v[120:123], v[160:163], v[192:195], v[120:123]
	v_mfma_f32_16x16x32_bf16 v[120:123], v[164:167], v[196:199], v[120:123]
	v_mfma_f32_16x16x32_bf16 v[108:111], v[152:155], v[200:203], v[108:111]
	v_mfma_f32_16x16x32_bf16 v[108:111], v[156:159], v[204:207], v[108:111]
	v_mfma_f32_16x16x32_bf16 v[104:107], v[160:163], v[200:203], v[104:107]
	v_mfma_f32_16x16x32_bf16 v[104:107], v[164:167], v[204:207], v[104:107]
	v_mfma_f32_16x16x32_bf16 v[92:95], v[152:155], v[208:211], v[92:95]
	v_mfma_f32_16x16x32_bf16 v[92:95], v[156:159], v[212:215], v[92:95]
	v_mfma_f32_16x16x32_bf16 v[88:91], v[160:163], v[208:211], v[88:91]
	v_mfma_f32_16x16x32_bf16 v[88:91], v[164:167], v[212:215], v[88:91]
	s_setprio 0
	s_setprio 1
	v_mfma_f32_16x16x32_bf16 v[116:119], v[168:171], v[184:187], v[116:119]
	v_mfma_f32_16x16x32_bf16 v[116:119], v[172:175], v[188:191], v[116:119]
	v_mfma_f32_16x16x32_bf16 v[112:115], v[176:179], v[184:187], v[112:115]
	v_mfma_f32_16x16x32_bf16 v[112:115], v[180:183], v[188:191], v[112:115]
	v_mfma_f32_16x16x32_bf16 v[100:103], v[168:171], v[192:195], v[100:103]
	v_mfma_f32_16x16x32_bf16 v[100:103], v[172:175], v[196:199], v[100:103]
	v_mfma_f32_16x16x32_bf16 v[96:99], v[176:179], v[192:195], v[96:99]
	v_mfma_f32_16x16x32_bf16 v[96:99], v[180:183], v[196:199], v[96:99]
	v_mfma_f32_16x16x32_bf16 v[84:87], v[168:171], v[200:203], v[84:87]
	v_mfma_f32_16x16x32_bf16 v[84:87], v[172:175], v[204:207], v[84:87]
	v_mfma_f32_16x16x32_bf16 v[80:83], v[176:179], v[200:203], v[80:83]
	v_mfma_f32_16x16x32_bf16 v[80:83], v[180:183], v[204:207], v[80:83]
	v_mfma_f32_16x16x32_bf16 v[76:79], v[168:171], v[208:211], v[76:79]
	v_mfma_f32_16x16x32_bf16 v[76:79], v[172:175], v[212:215], v[76:79]
	v_mfma_f32_16x16x32_bf16 v[72:75], v[176:179], v[208:211], v[72:75]
	v_mfma_f32_16x16x32_bf16 v[72:75], v[180:183], v[212:215], v[72:75]
	s_setprio 0
	s_barrier
	s_add_i32 s68, s68, s24
	s_mov_b32 m0, s68
	ds_read_b128 v[184:187], v150 offset:16384
	ds_read_b128 v[188:191], v150 offset:17408
	ds_read_b128 v[192:195], v150 offset:18432
	ds_read_b128 v[196:199], v150 offset:19456
	ds_read_b128 v[200:203], v150 offset:20480
	ds_read_b128 v[204:207], v150 offset:21504
	ds_read_b128 v[208:211], v150 offset:22528
	ds_read_b128 v[212:215], v150 offset:23552
	global_load_lds_dwordx4 v138, s[18:19]
	s_add_i32 m0, s68, 0x2000
	s_add_u32 s68, s18, 0x4000
	s_addc_u32 s69, s19, 0
	s_add_i32 s88, s88, s24
	global_load_lds_dwordx4 v142, s[18:19]
	s_mov_b32 m0, s88
	s_nop 0
	global_load_lds_dwordx4 v138, s[68:69]
	s_add_i32 m0, s88, 0x2000
	s_nop 0
	global_load_lds_dwordx4 v142, s[68:69]
	s_mov_b32 m0, s27
	s_nop 0
	global_load_lds_dwordx4 v136, s[20:21]
	s_mov_b32 m0, s28
	s_nop 0
	global_load_lds_dwordx4 v140, s[20:21]
	s_waitcnt vmcnt(8)
	s_waitcnt lgkmcnt(0)
	v_mfma_f32_16x16x32_bf16 v[68:71], v[152:155], v[184:187], v[68:71]
	v_mfma_f32_16x16x32_bf16 v[68:71], v[156:159], v[188:191], v[68:71]
	v_mfma_f32_16x16x32_bf16 v[64:67], v[160:163], v[184:187], v[64:67]
	v_mfma_f32_16x16x32_bf16 v[64:67], v[164:167], v[188:191], v[64:67]
	s_barrier
; #define PG8_STAGE(bufoff, gbase, voff) do { _Pragma("unroll") for (int _i = 0; _i < 2; ++_i) \
;         __builtin_amdgcn_global_load_lds((const unsigned*)((const char*)(gbase) + (voff)[_i]), (PG8_LAS unsigned*)(lds + (bufoff) + ldsw + _i * 8192), 16, 0, 0); } while (0)
; #define PG8_LDA(dst, b, h) do { _Pragma("unroll") for (int m = 0; m < 4; ++m) _Pragma("unroll") for (int k = 0; k < 2; ++k) dst[m][k] = *(const PG8_LAS bf16x8*)(lds + PG8_SA(b, h) + aoff + m * 2048 + k * 1024); } while (0)
; #define PG8_LDB(dst, b, h) do { _Pragma("unroll") for (int n = 0; n < 2; ++n) _Pragma("unroll") for (int k = 0; k < 2; ++k) dst[n][k] = *(const PG8_LAS bf16x8*)(lds + PG8_SB(b, h) + boff + n * 2048 + k * 1024); } while (0)
; #define PG8_MMA(ai, bj, At, Bt) do { __builtin_amdgcn_s_setprio(1); _Pragma("unroll") for (int m = 0; m < 4; ++m) _Pragma("unroll") for (int n = 0; n < 2; ++n) _Pragma("unroll") for (int k = 0; k < 2; ++k) \
;         acc[ai][bj][m][n] = __builtin_amdgcn_mfma_f32_16x16x32_bf16(Bt[n][k], At[m][k], acc[ai][bj][m][n], 0, 0, 0); __builtin_amdgcn_s_setprio(0); } while (0)
; #define PG8_WAIT_V(n) asm volatile("s_waitcnt vmcnt(" #n ")" ::: "memory")
; #define PG8_WAIT_L(n) asm volatile("s_waitcnt lgkmcnt(" #n ")" ::: "memory")
; #define PG8_BAR __builtin_amdgcn_s_barrier()
; #define PG8_SCHED __builtin_amdgcn_sched_barrier(0)
; template <class Epi, class Sched, bool ALIGN_EPI = false, bool SP2 = false, bool ABLK = false, bool BBLK = false>
; __device__ __forceinline__ void gemm_phase(PG8_LAS unsigned char* lds, const Gemm g, const Sched& S, const Epi& E) {
;     ...
;             PG8_WAIT_V(8); PG8_WAIT_L(0); PG8_BAR; PG8_MMA(1, 0, At, B0); PG8_MMA(1, 1, At, B1); PG8_BAR; PG8_SCHED;
;             PG8_LDB(B0, 1, 0); PG8_LDB(B1, 1, 1); PG8_SCHED; PG8_LDA(At, 1, 0); PG8_STAGE(PG8_SA(0, 1), a2 + hstepA, voffA);
;             PG8_WAIT_V(8); PG8_WAIT_L(0); PG8_BAR; PG8_MMA(0, 0, At, B0); PG8_MMA(0, 1, At, B1); PG8_BAR; PG8_SCHED;
;             PG8_LDA(At, 1, 1); PG8_STAGE(PG8_SB(1, 0), b3, voffB); PG8_STAGE(PG8_SB(1, 1), b3 + hstepB, voffB); PG8_STAGE(PG8_SA(1, 0), a3, voffA);
;             PG8_WAIT_V(8); PG8_WAIT_L(0); PG8_BAR; PG8_MMA(1, 0, At, B0); PG8_MMA(1, 1, At, B1); PG8_BAR; PG8_SCHED;
	s_setprio 1
	v_mfma_f32_16x16x32_bf16 v[60:63], v[152:155], v[192:195], v[60:63]
	v_mfma_f32_16x16x32_bf16 v[60:63], v[156:159], v[196:199], v[60:63]
	v_mfma_f32_16x16x32_bf16 v[56:59], v[160:163], v[192:195], v[56:59]
	v_mfma_f32_16x16x32_bf16 v[56:59], v[164:167], v[196:199], v[56:59]
	v_mfma_f32_16x16x32_bf16 v[44:47], v[152:155], v[200:203], v[44:47]
	v_mfma_f32_16x16x32_bf16 v[44:47], v[156:159], v[204:207], v[44:47]
	v_mfma_f32_16x16x32_bf16 v[40:43], v[160:163], v[200:203], v[40:43]
	v_mfma_f32_16x16x32_bf16 v[40:43], v[164:167], v[204:207], v[40:43]
	v_mfma_f32_16x16x32_bf16 v[24:27], v[152:155], v[208:211], v[24:27]
	v_mfma_f32_16x16x32_bf16 v[24:27], v[156:159], v[212:215], v[24:27]
	v_mfma_f32_16x16x32_bf16 v[20:23], v[160:163], v[208:211], v[20:23]
	v_mfma_f32_16x16x32_bf16 v[20:23], v[164:167], v[212:215], v[20:23]
	s_setprio 0
	s_setprio 1
	v_mfma_f32_16x16x32_bf16 v[52:55], v[168:171], v[184:187], v[52:55]
	v_mfma_f32_16x16x32_bf16 v[52:55], v[172:175], v[188:191], v[52:55]
	v_mfma_f32_16x16x32_bf16 v[48:51], v[176:179], v[184:187], v[48:51]
	v_mfma_f32_16x16x32_bf16 v[48:51], v[180:183], v[188:191], v[48:51]
	v_mfma_f32_16x16x32_bf16 v[32:35], v[168:171], v[192:195], v[32:35]
	v_mfma_f32_16x16x32_bf16 v[32:35], v[172:175], v[196:199], v[32:35]
	v_mfma_f32_16x16x32_bf16 v[28:31], v[176:179], v[192:195], v[28:31]
	v_mfma_f32_16x16x32_bf16 v[28:31], v[180:183], v[196:199], v[28:31]
	v_mfma_f32_16x16x32_bf16 v[16:19], v[168:171], v[200:203], v[16:19]
	v_mfma_f32_16x16x32_bf16 v[16:19], v[172:175], v[204:207], v[16:19]
	v_mfma_f32_16x16x32_bf16 v[12:15], v[176:179], v[200:203], v[12:15]
	v_mfma_f32_16x16x32_bf16 v[12:15], v[180:183], v[204:207], v[12:15]
	v_mfma_f32_16x16x32_bf16 v[8:11], v[168:171], v[208:211], v[8:11]
	v_mfma_f32_16x16x32_bf16 v[8:11], v[172:175], v[212:215], v[8:11]
	v_mfma_f32_16x16x32_bf16 v[4:7], v[176:179], v[208:211], v[4:7]
	v_mfma_f32_16x16x32_bf16 v[4:7], v[180:183], v[212:215], v[4:7]
	s_setprio 0
	s_barrier
	s_add_i32 s68, 0, 0x18000
	v_add_u32_e32 v36, s68, v148
	s_add_i32 s69, 0, 0x1c000
	ds_read_b128 v[152:155], v36
	ds_read_b128 v[156:159], v36 offset:1024
	ds_read_b128 v[160:163], v36 offset:2048
	ds_read_b128 v[164:167], v36 offset:3072
	v_add_u32_e32 v36, s69, v148
	ds_read_b128 v[168:171], v36
	ds_read_b128 v[172:175], v36 offset:1024
	ds_read_b128 v[176:179], v36 offset:2048
	ds_read_b128 v[180:183], v36 offset:3072
	s_add_u32 s20, s20, 0x4000
	s_addc_u32 s21, s21, 0
	s_mov_b32 m0, s29
	ds_read_b128 v[184:187], v150 offset:32768
	ds_read_b128 v[188:191], v150 offset:33792
	ds_read_b128 v[192:195], v150 offset:34816
	ds_read_b128 v[196:199], v150 offset:35840
	ds_read_b128 v[200:203], v150 offset:36864
	ds_read_b128 v[204:207], v150 offset:37888
	ds_read_b128 v[208:211], v150 offset:38912
	ds_read_b128 v[212:215], v150 offset:39936
	global_load_lds_dwordx4 v136, s[20:21]
	s_mov_b32 m0, s30
	s_nop 0
	global_load_lds_dwordx4 v140, s[20:21]
	s_waitcnt vmcnt(8)
	s_waitcnt lgkmcnt(0)
	v_mfma_f32_16x16x32_bf16 v[132:135], v[152:155], v[184:187], v[132:135]
	v_mfma_f32_16x16x32_bf16 v[132:135], v[156:159], v[188:191], v[132:135]
	v_mfma_f32_16x16x32_bf16 v[128:131], v[160:163], v[184:187], v[128:131]
	v_mfma_f32_16x16x32_bf16 v[128:131], v[164:167], v[188:191], v[128:131]
	s_barrier
	s_setprio 1
	v_mfma_f32_16x16x32_bf16 v[124:127], v[152:155], v[192:195], v[124:127]
	v_mfma_f32_16x16x32_bf16 v[124:127], v[156:159], v[196:199], v[124:127]
	v_mfma_f32_16x16x32_bf16 v[120:123], v[160:163], v[192:195], v[120:123]
	v_mfma_f32_16x16x32_bf16 v[120:123], v[164:167], v[196:199], v[120:123]
	v_mfma_f32_16x16x32_bf16 v[108:111], v[152:155], v[200:203], v[108:111]
	v_mfma_f32_16x16x32_bf16 v[108:111], v[156:159], v[204:207], v[108:111]
	v_mfma_f32_16x16x32_bf16 v[104:107], v[160:163], v[200:203], v[104:107]
	v_mfma_f32_16x16x32_bf16 v[104:107], v[164:167], v[204:207], v[104:107]
	v_mfma_f32_16x16x32_bf16 v[92:95], v[152:155], v[208:211], v[92:95]
	v_mfma_f32_16x16x32_bf16 v[92:95], v[156:159], v[212:215], v[92:95]
	v_mfma_f32_16x16x32_bf16 v[88:91], v[160:163], v[208:211], v[88:91]
	v_mfma_f32_16x16x32_bf16 v[88:91], v[164:167], v[212:215], v[88:91]
	s_setprio 0
	s_setprio 1
	v_mfma_f32_16x16x32_bf16 v[116:119], v[168:171], v[184:187], v[116:119]
	v_mfma_f32_16x16x32_bf16 v[116:119], v[172:175], v[188:191], v[116:119]
	v_mfma_f32_16x16x32_bf16 v[112:115], v[176:179], v[184:187], v[112:115]
	v_mfma_f32_16x16x32_bf16 v[112:115], v[180:183], v[188:191], v[112:115]
	v_mfma_f32_16x16x32_bf16 v[100:103], v[168:171], v[192:195], v[100:103]
	v_mfma_f32_16x16x32_bf16 v[100:103], v[172:175], v[196:199], v[100:103]
	v_mfma_f32_16x16x32_bf16 v[96:99], v[176:179], v[192:195], v[96:99]
	v_mfma_f32_16x16x32_bf16 v[96:99], v[180:183], v[196:199], v[96:99]
	v_mfma_f32_16x16x32_bf16 v[84:87], v[168:171], v[200:203], v[84:87]
	v_mfma_f32_16x16x32_bf16 v[84:87], v[172:175], v[204:207], v[84:87]
	v_mfma_f32_16x16x32_bf16 v[80:83], v[176:179], v[200:203], v[80:83]
	v_mfma_f32_16x16x32_bf16 v[80:83], v[180:183], v[204:207], v[80:83]
	v_mfma_f32_16x16x32_bf16 v[76:79], v[168:171], v[208:211], v[76:79]
	v_mfma_f32_16x16x32_bf16 v[76:79], v[172:175], v[212:215], v[76:79]
	v_mfma_f32_16x16x32_bf16 v[72:75], v[176:179], v[208:211], v[72:75]
	v_mfma_f32_16x16x32_bf16 v[72:75], v[180:183], v[212:215], v[72:75]
	s_setprio 0
	s_barrier
; #define PG8_STAGE(bufoff, gbase, voff) do { _Pragma("unroll") for (int _i = 0; _i < 2; ++_i) \
;         __builtin_amdgcn_global_load_lds((const unsigned*)((const char*)(gbase) + (voff)[_i]), (PG8_LAS unsigned*)(lds + (bufoff) + ldsw + _i * 8192), 16, 0, 0); } while (0)
; #define PG8_LDA(dst, b, h) do { _Pragma("unroll") for (int m = 0; m < 4; ++m) _Pragma("unroll") for (int k = 0; k < 2; ++k) dst[m][k] = *(const PG8_LAS bf16x8*)(lds + PG8_SA(b, h) + aoff + m * 2048 + k * 1024); } while (0)
; #define PG8_MMA(ai, bj, At, Bt) do { __builtin_amdgcn_s_setprio(1); _Pragma("unroll") for (int m = 0; m < 4; ++m) _Pragma("unroll") for (int n = 0; n < 2; ++n) _Pragma("unroll") for (int k = 0; k < 2; ++k) \
;         acc[ai][bj][m][n] = __builtin_amdgcn_mfma_f32_16x16x32_bf16(Bt[n][k], At[m][k], acc[ai][bj][m][n], 0, 0, 0); __builtin_amdgcn_s_setprio(0); } while (0)
; #define PG8_WAIT_V(n) asm volatile("s_waitcnt vmcnt(" #n ")" ::: "memory")
; #define PG8_WAIT_L(n) asm volatile("s_waitcnt lgkmcnt(" #n ")" ::: "memory")
; #define PG8_BAR __builtin_amdgcn_s_barrier()
; #define PG8_SCHED __builtin_amdgcn_sched_barrier(0)
; template <class Epi, class Sched, bool ALIGN_EPI = false, bool SP2 = false, bool ABLK = false, bool BBLK = false>
; __device__ __forceinline__ void gemm_phase(PG8_LAS unsigned char* lds, const Gemm g, const Sched& S, const Epi& E) {
;     ...
;         for (int t = 0; t < nt; t += 2) {
;             const bool last = (t == nt - 2);
;             const char* a1 = cA + (size_t)(t + 1) * kstepA;
;             const char* a2 = last ? nA : cA + (size_t)(t + 2) * kstepA; const char* b2 = last ? nB : cB + (size_t)(t + 2) * kstepB;
;             const char* a3 = a2 + kstepA; const char* b3 = b2 + kstepB;
;     ...
;             PG8_LDA(At, 1, 1); PG8_STAGE(PG8_SB(1, 0), b3, voffB); PG8_STAGE(PG8_SB(1, 1), b3 + hstepB, voffB); PG8_STAGE(PG8_SA(1, 0), a3, voffA);
;             PG8_WAIT_V(8); PG8_WAIT_L(0); PG8_BAR; PG8_MMA(1, 0, At, B0); PG8_MMA(1, 1, At, B1); PG8_BAR; PG8_SCHED;
	s_add_u32 s20, s18, 0x8000
	s_addc_u32 s21, s19, 0
	s_add_i32 s68, s68, s24
	s_mov_b32 m0, s68
	ds_read_b128 v[184:187], v150 offset:49152
	ds_read_b128 v[188:191], v150 offset:50176
	ds_read_b128 v[192:195], v150 offset:51200
	ds_read_b128 v[196:199], v150 offset:52224
	ds_read_b128 v[200:203], v150 offset:53248
	ds_read_b128 v[204:207], v150 offset:54272
	ds_read_b128 v[208:211], v150 offset:55296
	ds_read_b128 v[212:215], v150 offset:56320
	global_load_lds_dwordx4 v138, s[20:21]
	s_add_i32 m0, s68, 0x2000
	s_add_u32 s18, s18, 0xc000
	s_addc_u32 s19, s19, 0
	global_load_lds_dwordx4 v142, s[20:21]
	s_add_i32 s20, s69, s24
	s_mov_b32 m0, s20
	s_nop 0
	global_load_lds_dwordx4 v138, s[18:19]
	s_add_i32 m0, s20, 0x2000
	s_nop 0
	global_load_lds_dwordx4 v142, s[18:19]
	s_mov_b32 m0, s35
	s_nop 0
	global_load_lds_dwordx4 v136, s[16:17]
	s_mov_b32 m0, s70
	s_nop 0
	global_load_lds_dwordx4 v140, s[16:17]
	s_waitcnt vmcnt(8)
	s_waitcnt lgkmcnt(0)
	v_mfma_f32_16x16x32_bf16 v[68:71], v[152:155], v[184:187], v[68:71]
	v_mfma_f32_16x16x32_bf16 v[68:71], v[156:159], v[188:191], v[68:71]
	v_mfma_f32_16x16x32_bf16 v[64:67], v[160:163], v[184:187], v[64:67]
	v_mfma_f32_16x16x32_bf16 v[64:67], v[164:167], v[188:191], v[64:67]
	s_barrier
	s_setprio 1
	v_mfma_f32_16x16x32_bf16 v[60:63], v[152:155], v[192:195], v[60:63]
	v_mfma_f32_16x16x32_bf16 v[60:63], v[156:159], v[196:199], v[60:63]
	v_mfma_f32_16x16x32_bf16 v[56:59], v[160:163], v[192:195], v[56:59]
	v_mfma_f32_16x16x32_bf16 v[56:59], v[164:167], v[196:199], v[56:59]
	v_mfma_f32_16x16x32_bf16 v[44:47], v[152:155], v[200:203], v[44:47]
	v_mfma_f32_16x16x32_bf16 v[44:47], v[156:159], v[204:207], v[44:47]
	v_mfma_f32_16x16x32_bf16 v[40:43], v[160:163], v[200:203], v[40:43]
	v_mfma_f32_16x16x32_bf16 v[40:43], v[164:167], v[204:207], v[40:43]
	v_mfma_f32_16x16x32_bf16 v[24:27], v[152:155], v[208:211], v[24:27]
	v_mfma_f32_16x16x32_bf16 v[24:27], v[156:159], v[212:215], v[24:27]
	v_mfma_f32_16x16x32_bf16 v[20:23], v[160:163], v[208:211], v[20:23]
	v_mfma_f32_16x16x32_bf16 v[20:23], v[164:167], v[212:215], v[20:23]
	s_setprio 0
	s_setprio 1
	v_mfma_f32_16x16x32_bf16 v[52:55], v[168:171], v[184:187], v[52:55]
	v_mfma_f32_16x16x32_bf16 v[52:55], v[172:175], v[188:191], v[52:55]
	v_mfma_f32_16x16x32_bf16 v[48:51], v[176:179], v[184:187], v[48:51]
	v_mfma_f32_16x16x32_bf16 v[48:51], v[180:183], v[188:191], v[48:51]
	v_mfma_f32_16x16x32_bf16 v[32:35], v[168:171], v[192:195], v[32:35]
	v_mfma_f32_16x16x32_bf16 v[32:35], v[172:175], v[196:199], v[32:35]
	v_mfma_f32_16x16x32_bf16 v[28:31], v[176:179], v[192:195], v[28:31]
	v_mfma_f32_16x16x32_bf16 v[28:31], v[180:183], v[196:199], v[28:31]
	v_mfma_f32_16x16x32_bf16 v[16:19], v[168:171], v[200:203], v[16:19]
	v_mfma_f32_16x16x32_bf16 v[16:19], v[172:175], v[204:207], v[16:19]
	v_mfma_f32_16x16x32_bf16 v[12:15], v[176:179], v[200:203], v[12:15]
	v_mfma_f32_16x16x32_bf16 v[12:15], v[180:183], v[204:207], v[12:15]
	v_mfma_f32_16x16x32_bf16 v[8:11], v[168:171], v[208:211], v[8:11]
	v_mfma_f32_16x16x32_bf16 v[8:11], v[172:175], v[212:215], v[8:11]
	v_mfma_f32_16x16x32_bf16 v[4:7], v[176:179], v[208:211], v[4:7]
	v_mfma_f32_16x16x32_bf16 v[4:7], v[180:183], v[212:215], v[4:7]
	s_setprio 0
	s_barrier
	s_add_i32 s13, s13, 2
	s_add_u32 s10, s10, 0x10000
	s_addc_u32 s11, s11, 0
	s_add_u32 vcc_lo, vcc_lo, 0x10000
	s_addc_u32 vcc_hi, vcc_hi, 0
	s_cmpk_gt_u32 s13, 0x55
	s_cbranch_scc0 .LBB0_439
	s_and_b64 vcc, exec, s[6:7]
	s_cbranch_vccz .LBB0_442
	s_barrier

; #define PG8_STAGE(bufoff, gbase, voff) do { _Pragma("unroll") for (int _i = 0; _i < 2; ++_i) \
;         __builtin_amdgcn_global_load_lds((const unsigned*)((const char*)(gbase) + (voff)[_i]), (PG8_LAS unsigned*)(lds + (bufoff) + ldsw + _i * 8192), 16, 0, 0); } while (0)
; #define PG8_LDA(dst, b, h) do { _Pragma("unroll") for (int m = 0; m < 4; ++m) _Pragma("unroll") for (int k = 0; k < 2; ++k) dst[m][k] = *(const PG8_LAS bf16x8*)(lds + PG8_SA(b, h) + aoff + m * 2048 + k * 1024); } while (0)
; #define PG8_LDB(dst, b, h) do { _Pragma("unroll") for (int n = 0; n < 2; ++n) _Pragma("unroll") for (int k = 0; k < 2; ++k) dst[n][k] = *(const PG8_LAS bf16x8*)(lds + PG8_SB(b, h) + boff + n * 2048 + k * 1024); } while (0)
; #define PG8_MMA(ai, bj, At, Bt) do { __builtin_amdgcn_s_setprio(1); _Pragma("unroll") for (int m = 0; m < 4; ++m) _Pragma("unroll") for (int n = 0; n < 2; ++n) _Pragma("unroll") for (int k = 0; k < 2; ++k) \
;         acc[ai][bj][m][n] = __builtin_amdgcn_mfma_f32_16x16x32_bf16(Bt[n][k], At[m][k], acc[ai][bj][m][n], 0, 0, 0); __builtin_amdgcn_s_setprio(0); } while (0)
; #define PG8_WAIT_V(n) asm volatile("s_waitcnt vmcnt(" #n ")" ::: "memory")
; template <class Epi, class Sched, bool ALIGN_EPI = false, bool SP2 = false, bool ABLK = false, bool BBLK = false>
; __device__ __forceinline__ void gemm_phase(PG8_LAS unsigned char* lds, const Gemm g, const Sched& S, const Epi& E) {
;     ...
;         for (int t = 0; t < nt; t += 2) {
;             const bool last = (t == nt - 2);
;             const char* a1 = cA + (size_t)(t + 1) * kstepA;
;             const char* a2 = last ? nA : cA + (size_t)(t + 2) * kstepA; const char* b2 = last ? nB : cB + (size_t)(t + 2) * kstepB;
;             const char* a3 = a2 + kstepA; const char* b3 = b2 + kstepB;
;             if (last && has_next) S.a_ready(nxt);
;             if constexpr (SP2) {
;             PG8_LDB(B0, 0, 0); PG8_LDB(B1, 0, 1); PG8_SCHED; PG8_LDA(At, 0, 0); PG8_STAGE(PG8_SA(1, 1), a1 + hstepA, voffA);
;             PG8_WAIT_V(8); PG8_WAIT_L(0); PG8_BAR; PG8_MMA(0, 0, At, B0); PG8_MMA(0, 1, At, B1); PG8_BAR; PG8_SCHED;
;             PG8_LDA(At, 0, 1); PG8_STAGE(PG8_SB(0, 0), b2, voffB); PG8_STAGE(PG8_SB(0, 1), b2 + hstepB, voffB); PG8_STAGE(PG8_SA(0, 0), a2, voffA);
;             PG8_WAIT_V(8); PG8_WAIT_L(0); PG8_BAR; PG8_MMA(1, 0, At, B0); PG8_MMA(1, 1, At, B1); PG8_BAR; PG8_SCHED;
.LBB0_916:
	s_add_u32 s22, s20, 0x4000
	s_addc_u32 s23, s21, 0
	s_cmp_eq_u32 s13, 28
	s_cselect_b32 s26, s19, s22
	s_cselect_b32 s27, s1, s23
	s_cselect_b32 s24, s65, s70
	s_cselect_b32 s25, s9, s71
	s_add_u32 s22, s26, 0x8000
	s_addc_u32 s23, s27, 0
	s_add_i32 s68, 0, 0x10000
	v_add_u32_e32 v36, s68, v155
	s_add_i32 s77, 0, 0x14000
	ds_read_b128 v[150:153], v36
	ds_read_b128 v[158:161], v36 offset:1024
	ds_read_b128 v[162:165], v36 offset:2048
	ds_read_b128 v[166:169], v36 offset:3072
	v_add_u32_e32 v36, s77, v155
	ds_read_b128 v[170:173], v36
	ds_read_b128 v[174:177], v36 offset:1024
	ds_read_b128 v[178:181], v36 offset:2048
	ds_read_b128 v[182:185], v36 offset:3072
	s_add_i32 m0, s31, 0xc000
	ds_read_b128 v[186:189], v157
	ds_read_b128 v[190:193], v157 offset:1024
	ds_read_b128 v[194:197], v157 offset:2048
	ds_read_b128 v[198:201], v157 offset:3072
	ds_read_b128 v[202:205], v157 offset:4096
	ds_read_b128 v[206:209], v157 offset:5120
	ds_read_b128 v[210:213], v157 offset:6144
	ds_read_b128 v[214:217], v157 offset:7168
	global_load_lds_dwordx4 v146, s[20:21]
	s_add_i32 m0, s31, 0xe000
	s_nop 0
	global_load_lds_dwordx4 v148, s[20:21]
	s_waitcnt vmcnt(8)
	s_waitcnt lgkmcnt(0)
	v_mfma_f32_16x16x32_bf16 v[132:135], v[150:153], v[186:189], v[132:135]
	v_mfma_f32_16x16x32_bf16 v[132:135], v[158:161], v[190:193], v[132:135]
	v_mfma_f32_16x16x32_bf16 v[128:131], v[162:165], v[186:189], v[128:131]
	v_mfma_f32_16x16x32_bf16 v[128:131], v[166:169], v[190:193], v[128:131]
	s_barrier
	s_setprio 1
	v_mfma_f32_16x16x32_bf16 v[124:127], v[150:153], v[194:197], v[124:127]
	v_mfma_f32_16x16x32_bf16 v[124:127], v[158:161], v[198:201], v[124:127]
	v_mfma_f32_16x16x32_bf16 v[116:119], v[162:165], v[194:197], v[116:119]
	v_mfma_f32_16x16x32_bf16 v[116:119], v[166:169], v[198:201], v[116:119]
	v_mfma_f32_16x16x32_bf16 v[108:111], v[150:153], v[202:205], v[108:111]
	v_mfma_f32_16x16x32_bf16 v[108:111], v[158:161], v[206:209], v[108:111]
	v_mfma_f32_16x16x32_bf16 v[100:103], v[162:165], v[202:205], v[100:103]
	v_mfma_f32_16x16x32_bf16 v[100:103], v[166:169], v[206:209], v[100:103]
	v_mfma_f32_16x16x32_bf16 v[92:95], v[150:153], v[210:213], v[92:95]
	v_mfma_f32_16x16x32_bf16 v[92:95], v[158:161], v[214:217], v[92:95]
	v_mfma_f32_16x16x32_bf16 v[84:87], v[162:165], v[210:213], v[84:87]
	v_mfma_f32_16x16x32_bf16 v[84:87], v[166:169], v[214:217], v[84:87]
	s_setprio 0
	s_setprio 1
	v_mfma_f32_16x16x32_bf16 v[120:123], v[170:173], v[186:189], v[120:123]
	v_mfma_f32_16x16x32_bf16 v[120:123], v[174:177], v[190:193], v[120:123]
	v_mfma_f32_16x16x32_bf16 v[112:115], v[178:181], v[186:189], v[112:115]
	v_mfma_f32_16x16x32_bf16 v[112:115], v[182:185], v[190:193], v[112:115]
	v_mfma_f32_16x16x32_bf16 v[104:107], v[170:173], v[194:197], v[104:107]
	v_mfma_f32_16x16x32_bf16 v[104:107], v[174:177], v[198:201], v[104:107]
	v_mfma_f32_16x16x32_bf16 v[96:99], v[178:181], v[194:197], v[96:99]
	v_mfma_f32_16x16x32_bf16 v[96:99], v[182:185], v[198:201], v[96:99]
	v_mfma_f32_16x16x32_bf16 v[88:91], v[170:173], v[202:205], v[88:91]
	v_mfma_f32_16x16x32_bf16 v[88:91], v[174:177], v[206:209], v[88:91]
	v_mfma_f32_16x16x32_bf16 v[80:83], v[178:181], v[202:205], v[80:83]
	v_mfma_f32_16x16x32_bf16 v[80:83], v[182:185], v[206:209], v[80:83]
	v_mfma_f32_16x16x32_bf16 v[76:79], v[170:173], v[210:213], v[76:79]
	v_mfma_f32_16x16x32_bf16 v[76:79], v[174:177], v[214:217], v[76:79]
	v_mfma_f32_16x16x32_bf16 v[72:75], v[178:181], v[210:213], v[72:75]
	v_mfma_f32_16x16x32_bf16 v[72:75], v[182:185], v[214:217], v[72:75]
	s_setprio 0
	s_barrier
	s_add_i32 s68, s68, s29
	s_mov_b32 m0, s68
	ds_read_b128 v[186:189], v157 offset:16384
	ds_read_b128 v[190:193], v157 offset:17408
	ds_read_b128 v[194:197], v157 offset:18432
	ds_read_b128 v[198:201], v157 offset:19456
	ds_read_b128 v[202:205], v157 offset:20480
	ds_read_b128 v[206:209], v157 offset:21504
	ds_read_b128 v[210:213], v157 offset:22528
	ds_read_b128 v[214:217], v157 offset:23552
	global_load_lds_dwordx4 v140, s[24:25]
	s_add_i32 m0, s68, 0x2000
	s_add_u32 s68, s24, 0x4000
	s_addc_u32 s69, s25, 0
	s_add_i32 s77, s77, s29
	global_load_lds_dwordx4 v136, s[24:25]
	s_mov_b32 m0, s77
	s_nop 0
	global_load_lds_dwordx4 v140, s[68:69]
	s_add_i32 m0, s77, 0x2000
	s_nop 0
	global_load_lds_dwordx4 v136, s[68:69]
	s_mov_b32 m0, s31
	s_nop 0
	global_load_lds_dwordx4 v142, s[26:27]
	s_mov_b32 m0, s34
	s_nop 0
	global_load_lds_dwordx4 v138, s[26:27]
	s_waitcnt vmcnt(8)
	s_waitcnt lgkmcnt(0)
	v_mfma_f32_16x16x32_bf16 v[68:71], v[150:153], v[186:189], v[68:71]
	v_mfma_f32_16x16x32_bf16 v[68:71], v[158:161], v[190:193], v[68:71]
	v_mfma_f32_16x16x32_bf16 v[64:67], v[162:165], v[186:189], v[64:67]
	v_mfma_f32_16x16x32_bf16 v[64:67], v[166:169], v[190:193], v[64:67]
	s_barrier
; #define PG8_STAGE(bufoff, gbase, voff) do { _Pragma("unroll") for (int _i = 0; _i < 2; ++_i) \
;         __builtin_amdgcn_global_load_lds((const unsigned*)((const char*)(gbase) + (voff)[_i]), (PG8_LAS unsigned*)(lds + (bufoff) + ldsw + _i * 8192), 16, 0, 0); } while (0)
; #define PG8_LDA(dst, b, h) do { _Pragma("unroll") for (int m = 0; m < 4; ++m) _Pragma("unroll") for (int k = 0; k < 2; ++k) dst[m][k] = *(const PG8_LAS bf16x8*)(lds + PG8_SA(b, h) + aoff + m * 2048 + k * 1024); } while (0)
; #define PG8_LDB(dst, b, h) do { _Pragma("unroll") for (int n = 0; n < 2; ++n) _Pragma("unroll") for (int k = 0; k < 2; ++k) dst[n][k] = *(const PG8_LAS bf16x8*)(lds + PG8_SB(b, h) + boff + n * 2048 + k * 1024); } while (0)
; #define PG8_MMA(ai, bj, At, Bt) do { __builtin_amdgcn_s_setprio(1); _Pragma("unroll") for (int m = 0; m < 4; ++m) _Pragma("unroll") for (int n = 0; n < 2; ++n) _Pragma("unroll") for (int k = 0; k < 2; ++k) \
;         acc[ai][bj][m][n] = __builtin_amdgcn_mfma_f32_16x16x32_bf16(Bt[n][k], At[m][k], acc[ai][bj][m][n], 0, 0, 0); __builtin_amdgcn_s_setprio(0); } while (0)
; #define PG8_WAIT_V(n) asm volatile("s_waitcnt vmcnt(" #n ")" ::: "memory")
; #define PG8_WAIT_L(n) asm volatile("s_waitcnt lgkmcnt(" #n ")" ::: "memory")
; #define PG8_BAR __builtin_amdgcn_s_barrier()
; #define PG8_SCHED __builtin_amdgcn_sched_barrier(0)
; template <class Epi, class Sched, bool ALIGN_EPI = false, bool SP2 = false, bool ABLK = false, bool BBLK = false>
; __device__ __forceinline__ void gemm_phase(PG8_LAS unsigned char* lds, const Gemm g, const Sched& S, const Epi& E) {
;     ...
;             PG8_WAIT_V(8); PG8_WAIT_L(0); PG8_BAR; PG8_MMA(1, 0, At, B0); PG8_MMA(1, 1, At, B1); PG8_BAR; PG8_SCHED;
;             PG8_LDB(B0, 1, 0); PG8_LDB(B1, 1, 1); PG8_SCHED; PG8_LDA(At, 1, 0); PG8_STAGE(PG8_SA(0, 1), a2 + hstepA, voffA);
;             PG8_WAIT_V(8); PG8_WAIT_L(0); PG8_BAR; PG8_MMA(0, 0, At, B0); PG8_MMA(0, 1, At, B1); PG8_BAR; PG8_SCHED;
;             PG8_LDA(At, 1, 1); PG8_STAGE(PG8_SB(1, 0), b3, voffB); PG8_STAGE(PG8_SB(1, 1), b3 + hstepB, voffB); PG8_STAGE(PG8_SA(1, 0), a3, voffA);
;             PG8_WAIT_V(8); PG8_WAIT_L(0); PG8_BAR; PG8_MMA(1, 0, At, B0); PG8_MMA(1, 1, At, B1); PG8_BAR; PG8_SCHED;
	s_setprio 1
	v_mfma_f32_16x16x32_bf16 v[60:63], v[150:153], v[194:197], v[60:63]
	v_mfma_f32_16x16x32_bf16 v[60:63], v[158:161], v[198:201], v[60:63]
	v_mfma_f32_16x16x32_bf16 v[52:55], v[162:165], v[194:197], v[52:55]
	v_mfma_f32_16x16x32_bf16 v[52:55], v[166:169], v[198:201], v[52:55]
	v_mfma_f32_16x16x32_bf16 v[44:47], v[150:153], v[202:205], v[44:47]
	v_mfma_f32_16x16x32_bf16 v[44:47], v[158:161], v[206:209], v[44:47]
	v_mfma_f32_16x16x32_bf16 v[32:35], v[162:165], v[202:205], v[32:35]
	v_mfma_f32_16x16x32_bf16 v[32:35], v[166:169], v[206:209], v[32:35]
	v_mfma_f32_16x16x32_bf16 v[24:27], v[150:153], v[210:213], v[24:27]
	v_mfma_f32_16x16x32_bf16 v[24:27], v[158:161], v[214:217], v[24:27]
	v_mfma_f32_16x16x32_bf16 v[16:19], v[162:165], v[210:213], v[16:19]
	v_mfma_f32_16x16x32_bf16 v[16:19], v[166:169], v[214:217], v[16:19]
	s_setprio 0
	s_setprio 1
	v_mfma_f32_16x16x32_bf16 v[56:59], v[170:173], v[186:189], v[56:59]
	v_mfma_f32_16x16x32_bf16 v[56:59], v[174:177], v[190:193], v[56:59]
	v_mfma_f32_16x16x32_bf16 v[48:51], v[178:181], v[186:189], v[48:51]
	v_mfma_f32_16x16x32_bf16 v[48:51], v[182:185], v[190:193], v[48:51]
	v_mfma_f32_16x16x32_bf16 v[40:43], v[170:173], v[194:197], v[40:43]
	v_mfma_f32_16x16x32_bf16 v[40:43], v[174:177], v[198:201], v[40:43]
	v_mfma_f32_16x16x32_bf16 v[28:31], v[178:181], v[194:197], v[28:31]
	v_mfma_f32_16x16x32_bf16 v[28:31], v[182:185], v[198:201], v[28:31]
	v_mfma_f32_16x16x32_bf16 v[20:23], v[170:173], v[202:205], v[20:23]
	v_mfma_f32_16x16x32_bf16 v[20:23], v[174:177], v[206:209], v[20:23]
	v_mfma_f32_16x16x32_bf16 v[12:15], v[178:181], v[202:205], v[12:15]
	v_mfma_f32_16x16x32_bf16 v[12:15], v[182:185], v[206:209], v[12:15]
	v_mfma_f32_16x16x32_bf16 v[8:11], v[170:173], v[210:213], v[8:11]
	v_mfma_f32_16x16x32_bf16 v[8:11], v[174:177], v[214:217], v[8:11]
	v_mfma_f32_16x16x32_bf16 v[4:7], v[178:181], v[210:213], v[4:7]
	v_mfma_f32_16x16x32_bf16 v[4:7], v[182:185], v[214:217], v[4:7]
	s_setprio 0
	s_barrier
	s_add_i32 s68, 0, 0x18000
	v_add_u32_e32 v36, s68, v155
	s_add_i32 s69, 0, 0x1c000
	ds_read_b128 v[150:153], v36
	ds_read_b128 v[158:161], v36 offset:1024
	ds_read_b128 v[162:165], v36 offset:2048
	ds_read_b128 v[166:169], v36 offset:3072
	v_add_u32_e32 v36, s69, v155
	ds_read_b128 v[170:173], v36
	ds_read_b128 v[174:177], v36 offset:1024
	ds_read_b128 v[178:181], v36 offset:2048
	ds_read_b128 v[182:185], v36 offset:3072
	s_add_u32 s26, s26, 0x4000
	s_addc_u32 s27, s27, 0
	s_mov_b32 m0, s35
	ds_read_b128 v[186:189], v157 offset:32768
	ds_read_b128 v[190:193], v157 offset:33792
	ds_read_b128 v[194:197], v157 offset:34816
	ds_read_b128 v[198:201], v157 offset:35840
	ds_read_b128 v[202:205], v157 offset:36864
	ds_read_b128 v[206:209], v157 offset:37888
	ds_read_b128 v[210:213], v157 offset:38912
	ds_read_b128 v[214:217], v157 offset:39936
	global_load_lds_dwordx4 v142, s[26:27]
	s_mov_b32 m0, s36
	s_nop 0
	global_load_lds_dwordx4 v138, s[26:27]
	s_waitcnt vmcnt(8)
	s_waitcnt lgkmcnt(0)
	v_mfma_f32_16x16x32_bf16 v[132:135], v[150:153], v[186:189], v[132:135]
	v_mfma_f32_16x16x32_bf16 v[132:135], v[158:161], v[190:193], v[132:135]
	v_mfma_f32_16x16x32_bf16 v[128:131], v[162:165], v[186:189], v[128:131]
	v_mfma_f32_16x16x32_bf16 v[128:131], v[166:169], v[190:193], v[128:131]
	s_barrier
	s_setprio 1
	v_mfma_f32_16x16x32_bf16 v[124:127], v[150:153], v[194:197], v[124:127]
	v_mfma_f32_16x16x32_bf16 v[124:127], v[158:161], v[198:201], v[124:127]
	v_mfma_f32_16x16x32_bf16 v[116:119], v[162:165], v[194:197], v[116:119]
	v_mfma_f32_16x16x32_bf16 v[116:119], v[166:169], v[198:201], v[116:119]
	v_mfma_f32_16x16x32_bf16 v[108:111], v[150:153], v[202:205], v[108:111]
	v_mfma_f32_16x16x32_bf16 v[108:111], v[158:161], v[206:209], v[108:111]
	v_mfma_f32_16x16x32_bf16 v[100:103], v[162:165], v[202:205], v[100:103]
	v_mfma_f32_16x16x32_bf16 v[100:103], v[166:169], v[206:209], v[100:103]
	v_mfma_f32_16x16x32_bf16 v[92:95], v[150:153], v[210:213], v[92:95]
	v_mfma_f32_16x16x32_bf16 v[92:95], v[158:161], v[214:217], v[92:95]
	v_mfma_f32_16x16x32_bf16 v[84:87], v[162:165], v[210:213], v[84:87]
	v_mfma_f32_16x16x32_bf16 v[84:87], v[166:169], v[214:217], v[84:87]
	s_setprio 0
	s_setprio 1
	v_mfma_f32_16x16x32_bf16 v[120:123], v[170:173], v[186:189], v[120:123]
	v_mfma_f32_16x16x32_bf16 v[120:123], v[174:177], v[190:193], v[120:123]
	v_mfma_f32_16x16x32_bf16 v[112:115], v[178:181], v[186:189], v[112:115]
	v_mfma_f32_16x16x32_bf16 v[112:115], v[182:185], v[190:193], v[112:115]
	v_mfma_f32_16x16x32_bf16 v[104:107], v[170:173], v[194:197], v[104:107]
	v_mfma_f32_16x16x32_bf16 v[104:107], v[174:177], v[198:201], v[104:107]
	v_mfma_f32_16x16x32_bf16 v[96:99], v[178:181], v[194:197], v[96:99]
	v_mfma_f32_16x16x32_bf16 v[96:99], v[182:185], v[198:201], v[96:99]
	v_mfma_f32_16x16x32_bf16 v[88:91], v[170:173], v[202:205], v[88:91]
	v_mfma_f32_16x16x32_bf16 v[88:91], v[174:177], v[206:209], v[88:91]
	v_mfma_f32_16x16x32_bf16 v[80:83], v[178:181], v[202:205], v[80:83]
	v_mfma_f32_16x16x32_bf16 v[80:83], v[182:185], v[206:209], v[80:83]
	v_mfma_f32_16x16x32_bf16 v[76:79], v[170:173], v[210:213], v[76:79]
	v_mfma_f32_16x16x32_bf16 v[76:79], v[174:177], v[214:217], v[76:79]
	v_mfma_f32_16x16x32_bf16 v[72:75], v[178:181], v[210:213], v[72:75]
	v_mfma_f32_16x16x32_bf16 v[72:75], v[182:185], v[214:217], v[72:75]
	s_setprio 0
	s_barrier
; #define PG8_STAGE(bufoff, gbase, voff) do { _Pragma("unroll") for (int _i = 0; _i < 2; ++_i) \
;         __builtin_amdgcn_global_load_lds((const unsigned*)((const char*)(gbase) + (voff)[_i]), (PG8_LAS unsigned*)(lds + (bufoff) + ldsw + _i * 8192), 16, 0, 0); } while (0)
; #define PG8_LDA(dst, b, h) do { _Pragma("unroll") for (int m = 0; m < 4; ++m) _Pragma("unroll") for (int k = 0; k < 2; ++k) dst[m][k] = *(const PG8_LAS bf16x8*)(lds + PG8_SA(b, h) + aoff + m * 2048 + k * 1024); } while (0)
; #define PG8_MMA(ai, bj, At, Bt) do { __builtin_amdgcn_s_setprio(1); _Pragma("unroll") for (int m = 0; m < 4; ++m) _Pragma("unroll") for (int n = 0; n < 2; ++n) _Pragma("unroll") for (int k = 0; k < 2; ++k) \
;         acc[ai][bj][m][n] = __builtin_amdgcn_mfma_f32_16x16x32_bf16(Bt[n][k], At[m][k], acc[ai][bj][m][n], 0, 0, 0); __builtin_amdgcn_s_setprio(0); } while (0)
; #define PG8_WAIT_V(n) asm volatile("s_waitcnt vmcnt(" #n ")" ::: "memory")
; #define PG8_WAIT_L(n) asm volatile("s_waitcnt lgkmcnt(" #n ")" ::: "memory")
; #define PG8_BAR __builtin_amdgcn_s_barrier()
; #define PG8_SCHED __builtin_amdgcn_sched_barrier(0)
; template <class Epi, class Sched, bool ALIGN_EPI = false, bool SP2 = false, bool ABLK = false, bool BBLK = false>
; __device__ __forceinline__ void gemm_phase(PG8_LAS unsigned char* lds, const Gemm g, const Sched& S, const Epi& E) {
;     ...
;         for (int t = 0; t < nt; t += 2) {
;             const bool last = (t == nt - 2);
;             const char* a1 = cA + (size_t)(t + 1) * kstepA;
;             const char* a2 = last ? nA : cA + (size_t)(t + 2) * kstepA; const char* b2 = last ? nB : cB + (size_t)(t + 2) * kstepB;
;             const char* a3 = a2 + kstepA; const char* b3 = b2 + kstepB;
;     ...
;             PG8_LDA(At, 1, 1); PG8_STAGE(PG8_SB(1, 0), b3, voffB); PG8_STAGE(PG8_SB(1, 1), b3 + hstepB, voffB); PG8_STAGE(PG8_SA(1, 0), a3, voffA);
;             PG8_WAIT_V(8); PG8_WAIT_L(0); PG8_BAR; PG8_MMA(1, 0, At, B0); PG8_MMA(1, 1, At, B1); PG8_BAR; PG8_SCHED;
	s_add_u32 s26, s24, 0x8000
	s_addc_u32 s27, s25, 0
	s_add_i32 s68, s68, s29
	s_mov_b32 m0, s68
	ds_read_b128 v[186:189], v157 offset:49152
	ds_read_b128 v[190:193], v157 offset:50176
	ds_read_b128 v[194:197], v157 offset:51200
	ds_read_b128 v[198:201], v157 offset:52224
	ds_read_b128 v[202:205], v157 offset:53248
	ds_read_b128 v[206:209], v157 offset:54272
	ds_read_b128 v[210:213], v157 offset:55296
	ds_read_b128 v[214:217], v157 offset:56320
	global_load_lds_dwordx4 v140, s[26:27]
	s_add_i32 m0, s68, 0x2000
	s_add_u32 s24, s24, 0xc000
	s_addc_u32 s25, s25, 0
	global_load_lds_dwordx4 v136, s[26:27]
	s_add_i32 s26, s69, s29
	s_mov_b32 m0, s26
	s_nop 0
	global_load_lds_dwordx4 v140, s[24:25]
	s_add_i32 m0, s26, 0x2000
	s_nop 0
	global_load_lds_dwordx4 v136, s[24:25]
	s_mov_b32 m0, s37
	s_nop 0
	global_load_lds_dwordx4 v142, s[22:23]
	s_mov_b32 m0, s62
	s_nop 0
	global_load_lds_dwordx4 v138, s[22:23]
	s_waitcnt vmcnt(8)
	s_waitcnt lgkmcnt(0)
	v_mfma_f32_16x16x32_bf16 v[68:71], v[150:153], v[186:189], v[68:71]
	v_mfma_f32_16x16x32_bf16 v[68:71], v[158:161], v[190:193], v[68:71]
	v_mfma_f32_16x16x32_bf16 v[64:67], v[162:165], v[186:189], v[64:67]
	v_mfma_f32_16x16x32_bf16 v[64:67], v[166:169], v[190:193], v[64:67]
	s_barrier
	s_setprio 1
	v_mfma_f32_16x16x32_bf16 v[60:63], v[150:153], v[194:197], v[60:63]
	v_mfma_f32_16x16x32_bf16 v[60:63], v[158:161], v[198:201], v[60:63]
	v_mfma_f32_16x16x32_bf16 v[52:55], v[162:165], v[194:197], v[52:55]
	v_mfma_f32_16x16x32_bf16 v[52:55], v[166:169], v[198:201], v[52:55]
	v_mfma_f32_16x16x32_bf16 v[44:47], v[150:153], v[202:205], v[44:47]
	v_mfma_f32_16x16x32_bf16 v[44:47], v[158:161], v[206:209], v[44:47]
	v_mfma_f32_16x16x32_bf16 v[32:35], v[162:165], v[202:205], v[32:35]
	v_mfma_f32_16x16x32_bf16 v[32:35], v[166:169], v[206:209], v[32:35]
	v_mfma_f32_16x16x32_bf16 v[24:27], v[150:153], v[210:213], v[24:27]
	v_mfma_f32_16x16x32_bf16 v[24:27], v[158:161], v[214:217], v[24:27]
	v_mfma_f32_16x16x32_bf16 v[16:19], v[162:165], v[210:213], v[16:19]
	v_mfma_f32_16x16x32_bf16 v[16:19], v[166:169], v[214:217], v[16:19]
	s_setprio 0
	s_setprio 1
	v_mfma_f32_16x16x32_bf16 v[56:59], v[170:173], v[186:189], v[56:59]
	v_mfma_f32_16x16x32_bf16 v[56:59], v[174:177], v[190:193], v[56:59]
	v_mfma_f32_16x16x32_bf16 v[48:51], v[178:181], v[186:189], v[48:51]
	v_mfma_f32_16x16x32_bf16 v[48:51], v[182:185], v[190:193], v[48:51]
	v_mfma_f32_16x16x32_bf16 v[40:43], v[170:173], v[194:197], v[40:43]
	v_mfma_f32_16x16x32_bf16 v[40:43], v[174:177], v[198:201], v[40:43]
	v_mfma_f32_16x16x32_bf16 v[28:31], v[178:181], v[194:197], v[28:31]
	v_mfma_f32_16x16x32_bf16 v[28:31], v[182:185], v[198:201], v[28:31]
	v_mfma_f32_16x16x32_bf16 v[20:23], v[170:173], v[202:205], v[20:23]
	v_mfma_f32_16x16x32_bf16 v[20:23], v[174:177], v[206:209], v[20:23]
	v_mfma_f32_16x16x32_bf16 v[12:15], v[178:181], v[202:205], v[12:15]
	v_mfma_f32_16x16x32_bf16 v[12:15], v[182:185], v[206:209], v[12:15]
	v_mfma_f32_16x16x32_bf16 v[8:11], v[170:173], v[210:213], v[8:11]
	v_mfma_f32_16x16x32_bf16 v[8:11], v[174:177], v[214:217], v[8:11]
	v_mfma_f32_16x16x32_bf16 v[4:7], v[178:181], v[210:213], v[4:7]
	v_mfma_f32_16x16x32_bf16 v[4:7], v[182:185], v[214:217], v[4:7]
	s_setprio 0
	s_barrier
	s_add_i32 s13, s13, 2
	s_add_u32 s20, s20, 0x10000
	s_addc_u32 s21, s21, 0
	s_add_u32 s70, s70, 0x10000
	s_addc_u32 s71, s71, 0
	s_cmp_gt_u32 s13, 29
	s_cbranch_scc0 .LBB0_916
	s_and_b64 vcc, exec, s[6:7]
	s_cbranch_vccz .LBB0_919
	s_barrier

; #define PG8_STAGE(bufoff, gbase, voff) do { _Pragma("unroll") for (int _i = 0; _i < 2; ++_i) \
;         __builtin_amdgcn_global_load_lds((const unsigned*)((const char*)(gbase) + (voff)[_i]), (PG8_LAS unsigned*)(lds + (bufoff) + ldsw + _i * 8192), 16, 0, 0); } while (0)
; #define PG8_LDA(dst, b, h) do { _Pragma("unroll") for (int m = 0; m < 4; ++m) _Pragma("unroll") for (int k = 0; k < 2; ++k) dst[m][k] = *(const PG8_LAS bf16x8*)(lds + PG8_SA(b, h) + aoff + m * 2048 + k * 1024); } while (0)
; #define PG8_LDB(dst, b, h) do { _Pragma("unroll") for (int n = 0; n < 2; ++n) _Pragma("unroll") for (int k = 0; k < 2; ++k) dst[n][k] = *(const PG8_LAS bf16x8*)(lds + PG8_SB(b, h) + boff + n * 2048 + k * 1024); } while (0)
; #define PG8_MMA(ai, bj, At, Bt) do { __builtin_amdgcn_s_setprio(1); _Pragma("unroll") for (int m = 0; m < 4; ++m) _Pragma("unroll") for (int n = 0; n < 2; ++n) _Pragma("unroll") for (int k = 0; k < 2; ++k) \
;         acc[ai][bj][m][n] = __builtin_amdgcn_mfma_f32_16x16x32_bf16(Bt[n][k], At[m][k], acc[ai][bj][m][n], 0, 0, 0); __builtin_amdgcn_s_setprio(0); } while (0)
; #define PG8_WAIT_V(n) asm volatile("s_waitcnt vmcnt(" #n ")" ::: "memory")
; template <class Epi, class Sched, bool ALIGN_EPI = false, bool SP2 = false, bool ABLK = false, bool BBLK = false>
; __device__ __forceinline__ void gemm_phase(PG8_LAS unsigned char* lds, const Gemm g, const Sched& S, const Epi& E) {
;     ...
;         for (int t = 0; t < nt; t += 2) {
;             const bool last = (t == nt - 2);
;             const char* a1 = cA + (size_t)(t + 1) * kstepA;
;             const char* a2 = last ? nA : cA + (size_t)(t + 2) * kstepA; const char* b2 = last ? nB : cB + (size_t)(t + 2) * kstepB;
;             const char* a3 = a2 + kstepA; const char* b3 = b2 + kstepB;
;             if (last && has_next) S.a_ready(nxt);
;             if constexpr (SP2) {
;             PG8_LDB(B0, 0, 0); PG8_LDB(B1, 0, 1); PG8_SCHED; PG8_LDA(At, 0, 0); PG8_STAGE(PG8_SA(1, 1), a1 + hstepA, voffA);
;             PG8_WAIT_V(8); PG8_WAIT_L(0); PG8_BAR; PG8_MMA(0, 0, At, B0); PG8_MMA(0, 1, At, B1); PG8_BAR; PG8_SCHED;
;             PG8_LDA(At, 0, 1); PG8_STAGE(PG8_SB(0, 0), b2, voffB); PG8_STAGE(PG8_SB(0, 1), b2 + hstepB, voffB); PG8_STAGE(PG8_SA(0, 0), a2, voffA);
;             PG8_WAIT_V(8); PG8_WAIT_L(0); PG8_BAR; PG8_MMA(1, 0, At, B0); PG8_MMA(1, 1, At, B1); PG8_BAR; PG8_SCHED;
.LBB0_2111:
	s_add_u32 s24, s22, 0x4000
	s_addc_u32 s25, s23, 0
	s_cmp_eq_u32 s13, 28
	s_cselect_b32 s28, s17, s24
	s_cselect_b32 s29, s12, s25
	s_cselect_b32 s26, s77, s82
	s_cselect_b32 s27, s11, vcc_lo
	s_add_u32 s24, s28, 0x8000
	s_addc_u32 s25, s29, 0
	s_add_i32 s68, 0, 0x10000
	v_add_u32_e32 v151, s68, v148
	s_add_i32 s88, 0, 0x14000
	ds_read_b128 v[36:39], v151
	ds_read_b128 v[152:155], v151 offset:1024
	ds_read_b128 v[156:159], v151 offset:2048
	ds_read_b128 v[160:163], v151 offset:3072
	v_add_u32_e32 v151, s88, v148
	ds_read_b128 v[164:167], v151
	ds_read_b128 v[168:171], v151 offset:1024
	ds_read_b128 v[172:175], v151 offset:2048
	ds_read_b128 v[176:179], v151 offset:3072
	s_add_i32 m0, s9, 0xc000
	ds_read_b128 v[180:183], v150
	ds_read_b128 v[184:187], v150 offset:1024
	ds_read_b128 v[188:191], v150 offset:2048
	ds_read_b128 v[192:195], v150 offset:3072
	ds_read_b128 v[196:199], v150 offset:4096
	ds_read_b128 v[200:203], v150 offset:5120
	ds_read_b128 v[204:207], v150 offset:6144
	ds_read_b128 v[208:211], v150 offset:7168
	global_load_lds_dwordx4 v144, s[22:23]
	s_add_i32 m0, s9, 0xe000
	s_nop 0
	global_load_lds_dwordx4 v146, s[22:23]
	s_waitcnt vmcnt(8)
	s_waitcnt lgkmcnt(0)
	v_mfma_f32_16x16x32_bf16 v[132:135], v[36:39], v[180:183], v[132:135]
	v_mfma_f32_16x16x32_bf16 v[132:135], v[152:155], v[184:187], v[132:135]
	v_mfma_f32_16x16x32_bf16 v[128:131], v[156:159], v[180:183], v[128:131]
	v_mfma_f32_16x16x32_bf16 v[128:131], v[160:163], v[184:187], v[128:131]
	s_barrier
	s_setprio 1
	v_mfma_f32_16x16x32_bf16 v[124:127], v[36:39], v[188:191], v[124:127]
	v_mfma_f32_16x16x32_bf16 v[124:127], v[152:155], v[192:195], v[124:127]
	v_mfma_f32_16x16x32_bf16 v[120:123], v[156:159], v[188:191], v[120:123]
	v_mfma_f32_16x16x32_bf16 v[120:123], v[160:163], v[192:195], v[120:123]
	v_mfma_f32_16x16x32_bf16 v[108:111], v[36:39], v[196:199], v[108:111]
	v_mfma_f32_16x16x32_bf16 v[108:111], v[152:155], v[200:203], v[108:111]
	v_mfma_f32_16x16x32_bf16 v[104:107], v[156:159], v[196:199], v[104:107]
	v_mfma_f32_16x16x32_bf16 v[104:107], v[160:163], v[200:203], v[104:107]
	v_mfma_f32_16x16x32_bf16 v[92:95], v[36:39], v[204:207], v[92:95]
	v_mfma_f32_16x16x32_bf16 v[92:95], v[152:155], v[208:211], v[92:95]
	v_mfma_f32_16x16x32_bf16 v[88:91], v[156:159], v[204:207], v[88:91]
	v_mfma_f32_16x16x32_bf16 v[88:91], v[160:163], v[208:211], v[88:91]
	s_setprio 0
	s_setprio 1
	v_mfma_f32_16x16x32_bf16 v[116:119], v[164:167], v[180:183], v[116:119]
	v_mfma_f32_16x16x32_bf16 v[116:119], v[168:171], v[184:187], v[116:119]
	v_mfma_f32_16x16x32_bf16 v[112:115], v[172:175], v[180:183], v[112:115]
	v_mfma_f32_16x16x32_bf16 v[112:115], v[176:179], v[184:187], v[112:115]
	v_mfma_f32_16x16x32_bf16 v[100:103], v[164:167], v[188:191], v[100:103]
	v_mfma_f32_16x16x32_bf16 v[100:103], v[168:171], v[192:195], v[100:103]
	v_mfma_f32_16x16x32_bf16 v[96:99], v[172:175], v[188:191], v[96:99]
	v_mfma_f32_16x16x32_bf16 v[96:99], v[176:179], v[192:195], v[96:99]
	v_mfma_f32_16x16x32_bf16 v[84:87], v[164:167], v[196:199], v[84:87]
	v_mfma_f32_16x16x32_bf16 v[84:87], v[168:171], v[200:203], v[84:87]
	v_mfma_f32_16x16x32_bf16 v[80:83], v[172:175], v[196:199], v[80:83]
	v_mfma_f32_16x16x32_bf16 v[80:83], v[176:179], v[200:203], v[80:83]
	v_mfma_f32_16x16x32_bf16 v[76:79], v[164:167], v[204:207], v[76:79]
	v_mfma_f32_16x16x32_bf16 v[76:79], v[168:171], v[208:211], v[76:79]
	v_mfma_f32_16x16x32_bf16 v[72:75], v[172:175], v[204:207], v[72:75]
	v_mfma_f32_16x16x32_bf16 v[72:75], v[176:179], v[208:211], v[72:75]
	s_setprio 0
	s_barrier
	s_add_i32 s68, s68, s34
	s_mov_b32 m0, s68
	ds_read_b128 v[180:183], v150 offset:16384
	ds_read_b128 v[184:187], v150 offset:17408
	ds_read_b128 v[188:191], v150 offset:18432
	ds_read_b128 v[192:195], v150 offset:19456
	ds_read_b128 v[196:199], v150 offset:20480
	ds_read_b128 v[200:203], v150 offset:21504
	ds_read_b128 v[204:207], v150 offset:22528
	ds_read_b128 v[208:211], v150 offset:23552
	global_load_lds_dwordx4 v138, s[26:27]
	s_add_i32 m0, s68, 0x2000
	s_add_u32 s68, s26, 0x4000
	s_addc_u32 s69, s27, 0
	s_add_i32 s88, s88, s34
	global_load_lds_dwordx4 v142, s[26:27]
	s_mov_b32 m0, s88
	s_nop 0
	global_load_lds_dwordx4 v138, s[68:69]
	s_add_i32 m0, s88, 0x2000
	s_nop 0
	global_load_lds_dwordx4 v142, s[68:69]
	s_mov_b32 m0, s9
	s_nop 0
	global_load_lds_dwordx4 v136, s[28:29]
	s_mov_b32 m0, s35
	s_nop 0
	global_load_lds_dwordx4 v140, s[28:29]
	s_waitcnt vmcnt(8)
	s_waitcnt lgkmcnt(0)
	v_mfma_f32_16x16x32_bf16 v[68:71], v[36:39], v[180:183], v[68:71]
	v_mfma_f32_16x16x32_bf16 v[68:71], v[152:155], v[184:187], v[68:71]
	v_mfma_f32_16x16x32_bf16 v[64:67], v[156:159], v[180:183], v[64:67]
	v_mfma_f32_16x16x32_bf16 v[64:67], v[160:163], v[184:187], v[64:67]
	s_barrier
; #define PG8_STAGE(bufoff, gbase, voff) do { _Pragma("unroll") for (int _i = 0; _i < 2; ++_i) \
;         __builtin_amdgcn_global_load_lds((const unsigned*)((const char*)(gbase) + (voff)[_i]), (PG8_LAS unsigned*)(lds + (bufoff) + ldsw + _i * 8192), 16, 0, 0); } while (0)
; #define PG8_LDA(dst, b, h) do { _Pragma("unroll") for (int m = 0; m < 4; ++m) _Pragma("unroll") for (int k = 0; k < 2; ++k) dst[m][k] = *(const PG8_LAS bf16x8*)(lds + PG8_SA(b, h) + aoff + m * 2048 + k * 1024); } while (0)
; #define PG8_LDB(dst, b, h) do { _Pragma("unroll") for (int n = 0; n < 2; ++n) _Pragma("unroll") for (int k = 0; k < 2; ++k) dst[n][k] = *(const PG8_LAS bf16x8*)(lds + PG8_SB(b, h) + boff + n * 2048 + k * 1024); } while (0)
; #define PG8_MMA(ai, bj, At, Bt) do { __builtin_amdgcn_s_setprio(1); _Pragma("unroll") for (int m = 0; m < 4; ++m) _Pragma("unroll") for (int n = 0; n < 2; ++n) _Pragma("unroll") for (int k = 0; k < 2; ++k) \
;         acc[ai][bj][m][n] = __builtin_amdgcn_mfma_f32_16x16x32_bf16(Bt[n][k], At[m][k], acc[ai][bj][m][n], 0, 0, 0); __builtin_amdgcn_s_setprio(0); } while (0)
; #define PG8_WAIT_V(n) asm volatile("s_waitcnt vmcnt(" #n ")" ::: "memory")
; #define PG8_WAIT_L(n) asm volatile("s_waitcnt lgkmcnt(" #n ")" ::: "memory")
; #define PG8_BAR __builtin_amdgcn_s_barrier()
; #define PG8_SCHED __builtin_amdgcn_sched_barrier(0)
; template <class Epi, class Sched, bool ALIGN_EPI = false, bool SP2 = false, bool ABLK = false, bool BBLK = false>
; __device__ __forceinline__ void gemm_phase(PG8_LAS unsigned char* lds, const Gemm g, const Sched& S, const Epi& E) {
;     ...
;             PG8_WAIT_V(8); PG8_WAIT_L(0); PG8_BAR; PG8_MMA(1, 0, At, B0); PG8_MMA(1, 1, At, B1); PG8_BAR; PG8_SCHED;
;             PG8_LDB(B0, 1, 0); PG8_LDB(B1, 1, 1); PG8_SCHED; PG8_LDA(At, 1, 0); PG8_STAGE(PG8_SA(0, 1), a2 + hstepA, voffA);
;             PG8_WAIT_V(8); PG8_WAIT_L(0); PG8_BAR; PG8_MMA(0, 0, At, B0); PG8_MMA(0, 1, At, B1); PG8_BAR; PG8_SCHED;
;             PG8_LDA(At, 1, 1); PG8_STAGE(PG8_SB(1, 0), b3, voffB); PG8_STAGE(PG8_SB(1, 1), b3 + hstepB, voffB); PG8_STAGE(PG8_SA(1, 0), a3, voffA);
;             PG8_WAIT_V(8); PG8_WAIT_L(0); PG8_BAR; PG8_MMA(1, 0, At, B0); PG8_MMA(1, 1, At, B1); PG8_BAR; PG8_SCHED;
	s_setprio 1
	v_mfma_f32_16x16x32_bf16 v[60:63], v[36:39], v[188:191], v[60:63]
	v_mfma_f32_16x16x32_bf16 v[60:63], v[152:155], v[192:195], v[60:63]
	v_mfma_f32_16x16x32_bf16 v[56:59], v[156:159], v[188:191], v[56:59]
	v_mfma_f32_16x16x32_bf16 v[56:59], v[160:163], v[192:195], v[56:59]
	v_mfma_f32_16x16x32_bf16 v[44:47], v[36:39], v[196:199], v[44:47]
	v_mfma_f32_16x16x32_bf16 v[44:47], v[152:155], v[200:203], v[44:47]
	v_mfma_f32_16x16x32_bf16 v[40:43], v[156:159], v[196:199], v[40:43]
	v_mfma_f32_16x16x32_bf16 v[40:43], v[160:163], v[200:203], v[40:43]
	v_mfma_f32_16x16x32_bf16 v[24:27], v[36:39], v[204:207], v[24:27]
	v_mfma_f32_16x16x32_bf16 v[24:27], v[152:155], v[208:211], v[24:27]
	v_mfma_f32_16x16x32_bf16 v[20:23], v[156:159], v[204:207], v[20:23]
	v_mfma_f32_16x16x32_bf16 v[20:23], v[160:163], v[208:211], v[20:23]
	s_setprio 0
	s_setprio 1
	v_mfma_f32_16x16x32_bf16 v[48:51], v[172:175], v[180:183], v[48:51]
	v_mfma_f32_16x16x32_bf16 v[32:35], v[164:167], v[188:191], v[32:35]
	v_mfma_f32_16x16x32_bf16 v[28:31], v[172:175], v[188:191], v[28:31]
	v_mfma_f32_16x16x32_bf16 v[16:19], v[164:167], v[196:199], v[16:19]
	v_mfma_f32_16x16x32_bf16 v[12:15], v[172:175], v[196:199], v[12:15]
	v_mfma_f32_16x16x32_bf16 v[8:11], v[164:167], v[204:207], v[8:11]
	v_mfma_f32_16x16x32_bf16 v[4:7], v[172:175], v[204:207], v[4:7]
	v_mfma_f32_16x16x32_bf16 v[36:39], v[164:167], v[180:183], v[52:55]
	v_mfma_f32_16x16x32_bf16 v[48:51], v[176:179], v[184:187], v[48:51]
	v_mfma_f32_16x16x32_bf16 v[32:35], v[168:171], v[192:195], v[32:35]
	v_mfma_f32_16x16x32_bf16 v[28:31], v[176:179], v[192:195], v[28:31]
	v_mfma_f32_16x16x32_bf16 v[16:19], v[168:171], v[200:203], v[16:19]
	v_mfma_f32_16x16x32_bf16 v[12:15], v[176:179], v[200:203], v[12:15]
	v_mfma_f32_16x16x32_bf16 v[8:11], v[168:171], v[208:211], v[8:11]
	v_mfma_f32_16x16x32_bf16 v[4:7], v[176:179], v[208:211], v[4:7]
	v_mfma_f32_16x16x32_bf16 v[36:39], v[168:171], v[184:187], v[36:39]
	s_setprio 0
	s_barrier
	s_add_i32 s68, 0, 0x18000
	v_add_u32_e32 v151, s68, v148
	s_add_i32 s69, 0, 0x1c000
	ds_read_b128 v[52:55], v151
	ds_read_b128 v[152:155], v151 offset:1024
	ds_read_b128 v[156:159], v151 offset:2048
	ds_read_b128 v[160:163], v151 offset:3072
	v_add_u32_e32 v151, s69, v148
	ds_read_b128 v[164:167], v151
	ds_read_b128 v[168:171], v151 offset:1024
	ds_read_b128 v[172:175], v151 offset:2048
	ds_read_b128 v[176:179], v151 offset:3072
	s_add_u32 s28, s28, 0x4000
	s_addc_u32 s29, s29, 0
	s_mov_b32 m0, s36
	ds_read_b128 v[180:183], v150 offset:32768
	ds_read_b128 v[184:187], v150 offset:33792
	ds_read_b128 v[188:191], v150 offset:34816
	ds_read_b128 v[192:195], v150 offset:35840
	ds_read_b128 v[196:199], v150 offset:36864
	ds_read_b128 v[200:203], v150 offset:37888
	ds_read_b128 v[204:207], v150 offset:38912
	ds_read_b128 v[208:211], v150 offset:39936
	global_load_lds_dwordx4 v136, s[28:29]
	s_mov_b32 m0, s37
	s_nop 0
	global_load_lds_dwordx4 v140, s[28:29]
	s_waitcnt vmcnt(8)
	s_waitcnt lgkmcnt(0)
	v_mfma_f32_16x16x32_bf16 v[132:135], v[52:55], v[180:183], v[132:135]
	v_mfma_f32_16x16x32_bf16 v[132:135], v[152:155], v[184:187], v[132:135]
	v_mfma_f32_16x16x32_bf16 v[128:131], v[156:159], v[180:183], v[128:131]
	v_mfma_f32_16x16x32_bf16 v[128:131], v[160:163], v[184:187], v[128:131]
	s_barrier
	s_setprio 1
	v_mfma_f32_16x16x32_bf16 v[124:127], v[52:55], v[188:191], v[124:127]
	v_mfma_f32_16x16x32_bf16 v[124:127], v[152:155], v[192:195], v[124:127]
	v_mfma_f32_16x16x32_bf16 v[120:123], v[156:159], v[188:191], v[120:123]
	v_mfma_f32_16x16x32_bf16 v[120:123], v[160:163], v[192:195], v[120:123]
	v_mfma_f32_16x16x32_bf16 v[108:111], v[52:55], v[196:199], v[108:111]
	v_mfma_f32_16x16x32_bf16 v[108:111], v[152:155], v[200:203], v[108:111]
	v_mfma_f32_16x16x32_bf16 v[104:107], v[156:159], v[196:199], v[104:107]
	v_mfma_f32_16x16x32_bf16 v[104:107], v[160:163], v[200:203], v[104:107]
	v_mfma_f32_16x16x32_bf16 v[92:95], v[52:55], v[204:207], v[92:95]
	v_mfma_f32_16x16x32_bf16 v[92:95], v[152:155], v[208:211], v[92:95]
	v_mfma_f32_16x16x32_bf16 v[88:91], v[156:159], v[204:207], v[88:91]
	v_mfma_f32_16x16x32_bf16 v[88:91], v[160:163], v[208:211], v[88:91]
	s_setprio 0
	s_setprio 1
	v_mfma_f32_16x16x32_bf16 v[116:119], v[164:167], v[180:183], v[116:119]
	v_mfma_f32_16x16x32_bf16 v[116:119], v[168:171], v[184:187], v[116:119]
	v_mfma_f32_16x16x32_bf16 v[112:115], v[172:175], v[180:183], v[112:115]
	v_mfma_f32_16x16x32_bf16 v[112:115], v[176:179], v[184:187], v[112:115]
	v_mfma_f32_16x16x32_bf16 v[100:103], v[164:167], v[188:191], v[100:103]
	v_mfma_f32_16x16x32_bf16 v[100:103], v[168:171], v[192:195], v[100:103]
	v_mfma_f32_16x16x32_bf16 v[96:99], v[172:175], v[188:191], v[96:99]
	v_mfma_f32_16x16x32_bf16 v[96:99], v[176:179], v[192:195], v[96:99]
	v_mfma_f32_16x16x32_bf16 v[84:87], v[164:167], v[196:199], v[84:87]
	v_mfma_f32_16x16x32_bf16 v[84:87], v[168:171], v[200:203], v[84:87]
	v_mfma_f32_16x16x32_bf16 v[80:83], v[172:175], v[196:199], v[80:83]
	v_mfma_f32_16x16x32_bf16 v[80:83], v[176:179], v[200:203], v[80:83]
	v_mfma_f32_16x16x32_bf16 v[76:79], v[164:167], v[204:207], v[76:79]
	v_mfma_f32_16x16x32_bf16 v[76:79], v[168:171], v[208:211], v[76:79]
	v_mfma_f32_16x16x32_bf16 v[72:75], v[172:175], v[204:207], v[72:75]
	v_mfma_f32_16x16x32_bf16 v[72:75], v[176:179], v[208:211], v[72:75]
	s_setprio 0
	s_barrier
; #define PG8_STAGE(bufoff, gbase, voff) do { _Pragma("unroll") for (int _i = 0; _i < 2; ++_i) \
;         __builtin_amdgcn_global_load_lds((const unsigned*)((const char*)(gbase) + (voff)[_i]), (PG8_LAS unsigned*)(lds + (bufoff) + ldsw + _i * 8192), 16, 0, 0); } while (0)
; #define PG8_LDA(dst, b, h) do { _Pragma("unroll") for (int m = 0; m < 4; ++m) _Pragma("unroll") for (int k = 0; k < 2; ++k) dst[m][k] = *(const PG8_LAS bf16x8*)(lds + PG8_SA(b, h) + aoff + m * 2048 + k * 1024); } while (0)
; #define PG8_MMA(ai, bj, At, Bt) do { __builtin_amdgcn_s_setprio(1); _Pragma("unroll") for (int m = 0; m < 4; ++m) _Pragma("unroll") for (int n = 0; n < 2; ++n) _Pragma("unroll") for (int k = 0; k < 2; ++k) \
;         acc[ai][bj][m][n] = __builtin_amdgcn_mfma_f32_16x16x32_bf16(Bt[n][k], At[m][k], acc[ai][bj][m][n], 0, 0, 0); __builtin_amdgcn_s_setprio(0); } while (0)
; #define PG8_WAIT_V(n) asm volatile("s_waitcnt vmcnt(" #n ")" ::: "memory")
; #define PG8_WAIT_L(n) asm volatile("s_waitcnt lgkmcnt(" #n ")" ::: "memory")
; #define PG8_BAR __builtin_amdgcn_s_barrier()
; #define PG8_SCHED __builtin_amdgcn_sched_barrier(0)
; template <class Epi, class Sched, bool ALIGN_EPI = false, bool SP2 = false, bool ABLK = false, bool BBLK = false>
; __device__ __forceinline__ void gemm_phase(PG8_LAS unsigned char* lds, const Gemm g, const Sched& S, const Epi& E) {
;     ...
;         for (int t = 0; t < nt; t += 2) {
;             const bool last = (t == nt - 2);
;             const char* a1 = cA + (size_t)(t + 1) * kstepA;
;             const char* a2 = last ? nA : cA + (size_t)(t + 2) * kstepA; const char* b2 = last ? nB : cB + (size_t)(t + 2) * kstepB;
;             const char* a3 = a2 + kstepA; const char* b3 = b2 + kstepB;
;     ...
;             PG8_LDA(At, 1, 1); PG8_STAGE(PG8_SB(1, 0), b3, voffB); PG8_STAGE(PG8_SB(1, 1), b3 + hstepB, voffB); PG8_STAGE(PG8_SA(1, 0), a3, voffA);
;             PG8_WAIT_V(8); PG8_WAIT_L(0); PG8_BAR; PG8_MMA(1, 0, At, B0); PG8_MMA(1, 1, At, B1); PG8_BAR; PG8_SCHED;
	s_add_u32 s28, s26, 0x8000
	s_addc_u32 s29, s27, 0
	s_add_i32 s68, s68, s34
	s_mov_b32 m0, s68
	ds_read_b128 v[180:183], v150 offset:49152
	ds_read_b128 v[184:187], v150 offset:50176
	ds_read_b128 v[188:191], v150 offset:51200
	ds_read_b128 v[192:195], v150 offset:52224
	ds_read_b128 v[196:199], v150 offset:53248
	ds_read_b128 v[200:203], v150 offset:54272
	ds_read_b128 v[204:207], v150 offset:55296
	ds_read_b128 v[208:211], v150 offset:56320
	global_load_lds_dwordx4 v138, s[28:29]
	s_add_i32 m0, s68, 0x2000
	s_add_u32 s26, s26, 0xc000
	s_addc_u32 s27, s27, 0
	global_load_lds_dwordx4 v142, s[28:29]
	s_add_i32 s28, s69, s34
	s_mov_b32 m0, s28
	s_nop 0
	global_load_lds_dwordx4 v138, s[26:27]
	s_add_i32 m0, s28, 0x2000
	s_nop 0
	global_load_lds_dwordx4 v142, s[26:27]
	s_mov_b32 m0, s64
	s_nop 0
	global_load_lds_dwordx4 v136, s[24:25]
	s_mov_b32 m0, s65
	s_nop 0
	global_load_lds_dwordx4 v140, s[24:25]
	s_waitcnt vmcnt(8)
	s_waitcnt lgkmcnt(0)
	v_mfma_f32_16x16x32_bf16 v[68:71], v[52:55], v[180:183], v[68:71]
	v_mfma_f32_16x16x32_bf16 v[68:71], v[152:155], v[184:187], v[68:71]
	v_mfma_f32_16x16x32_bf16 v[64:67], v[156:159], v[180:183], v[64:67]
	v_mfma_f32_16x16x32_bf16 v[64:67], v[160:163], v[184:187], v[64:67]
	s_barrier
	s_setprio 1
	v_mfma_f32_16x16x32_bf16 v[60:63], v[52:55], v[188:191], v[60:63]
	v_mfma_f32_16x16x32_bf16 v[60:63], v[152:155], v[192:195], v[60:63]
	v_mfma_f32_16x16x32_bf16 v[56:59], v[156:159], v[188:191], v[56:59]
	v_mfma_f32_16x16x32_bf16 v[56:59], v[160:163], v[192:195], v[56:59]
	v_mfma_f32_16x16x32_bf16 v[44:47], v[52:55], v[196:199], v[44:47]
	v_mfma_f32_16x16x32_bf16 v[44:47], v[152:155], v[200:203], v[44:47]
	v_mfma_f32_16x16x32_bf16 v[40:43], v[156:159], v[196:199], v[40:43]
	v_mfma_f32_16x16x32_bf16 v[40:43], v[160:163], v[200:203], v[40:43]
	v_mfma_f32_16x16x32_bf16 v[24:27], v[52:55], v[204:207], v[24:27]
	v_mfma_f32_16x16x32_bf16 v[24:27], v[152:155], v[208:211], v[24:27]
	v_mfma_f32_16x16x32_bf16 v[20:23], v[156:159], v[204:207], v[20:23]
	v_mfma_f32_16x16x32_bf16 v[20:23], v[160:163], v[208:211], v[20:23]
	s_setprio 0
	s_setprio 1
	v_mfma_f32_16x16x32_bf16 v[36:39], v[164:167], v[180:183], v[36:39]
	v_mfma_f32_16x16x32_bf16 v[52:55], v[168:171], v[184:187], v[36:39]
	v_mfma_f32_16x16x32_bf16 v[36:39], v[172:175], v[180:183], v[48:51]
	v_mfma_f32_16x16x32_bf16 v[32:35], v[164:167], v[188:191], v[32:35]
	v_mfma_f32_16x16x32_bf16 v[28:31], v[172:175], v[188:191], v[28:31]
	v_mfma_f32_16x16x32_bf16 v[16:19], v[164:167], v[196:199], v[16:19]
	v_mfma_f32_16x16x32_bf16 v[12:15], v[172:175], v[196:199], v[12:15]
	v_mfma_f32_16x16x32_bf16 v[8:11], v[164:167], v[204:207], v[8:11]
	v_mfma_f32_16x16x32_bf16 v[4:7], v[172:175], v[204:207], v[4:7]
	v_mfma_f32_16x16x32_bf16 v[48:51], v[176:179], v[184:187], v[36:39]
	v_mfma_f32_16x16x32_bf16 v[32:35], v[168:171], v[192:195], v[32:35]
	v_mfma_f32_16x16x32_bf16 v[28:31], v[176:179], v[192:195], v[28:31]
	v_mfma_f32_16x16x32_bf16 v[16:19], v[168:171], v[200:203], v[16:19]
	v_mfma_f32_16x16x32_bf16 v[12:15], v[176:179], v[200:203], v[12:15]
	v_mfma_f32_16x16x32_bf16 v[8:11], v[168:171], v[208:211], v[8:11]
	v_mfma_f32_16x16x32_bf16 v[4:7], v[176:179], v[208:211], v[4:7]
	s_setprio 0
	s_barrier
	s_add_i32 s13, s13, 2
	s_add_u32 s22, s22, 0x10000
	s_addc_u32 s23, s23, 0
	s_add_u32 s82, s82, 0x10000
	s_addc_u32 vcc_lo, vcc_lo, 0
	s_cmp_gt_u32 s13, 29
	s_cbranch_scc0 .LBB0_2111
	s_and_b64 vcc, exec, s[6:7]
	s_movk_i32 s77, 0x1000
	s_cbranch_vccz .LBB0_2114
	s_barrier
